# 64-byte alignment of the GEMM K-loop and expert U/V loop heads
# speedup vs baseline: 1.0302x; 1.0002x over previous
.LBB0_71:
	s_ashr_i32 s36, s31, 2
	s_and_b32 s36, s36, -8
	s_or_b32 s36, s36, s3
	s_ashr_i32 s37, s36, 31
	s_lshr_b32 s37, s37, 29
	s_add_i32 s37, s36, s37
	s_ashr_i32 s43, s37, 3
	s_and_b32 s37, s37, 0x1ffff8
	s_bfe_u32 s5, s31, 0x20003
	s_sub_i32 s42, s36, s37
	s_lshl_b32 s37, s43, 2
	s_lshl_b32 s33, s5, 8
	s_or_b32 s37, s37, s5
	s_lshl_b32 s5, s42, 11
	s_lshl_b32 s42, s31, 8
	s_and_b32 s42, s42, 0x700
	s_or_b32 s42, s5, s42
	v_add_u32_e32 v0, s42, v187
	v_ashrrev_i32_e32 v1, 31, v0
	v_lshl_add_u32 v2, s37, 8, v187
	v_lshlrev_b64 v[0:1], 12, v[0:1]
	v_ashrrev_i32_e32 v3, 31, v2
	v_readfirstlane_b32 s5, v188
	v_lshl_add_u64 v[0:1], v[146:147], 0, v[0:1]
	v_lshlrev_b64 v[2:3], 12, v[2:3]
	s_add_i32 m0, s5, -16
	v_readfirstlane_b32 s5, v200
	v_lshl_add_u64 v[2:3], v[148:149], 0, v[2:3]
	global_load_lds_dwordx4 v[0:1], off
	s_add_i32 m0, s5, -16
	v_readfirstlane_b32 s5, v201
	global_load_lds_dwordx4 v[2:3], off
	v_lshl_add_u64 v[4:5], v[0:1], 0, s[6:7]
	s_add_i32 m0, s5, -16
	v_readfirstlane_b32 s5, v202
	global_load_lds_dwordx4 v[4:5], off
	v_lshl_add_u64 v[4:5], v[2:3], 0, s[6:7]
	s_add_i32 m0, s5, -16
	v_readfirstlane_b32 s5, v203
	global_load_lds_dwordx4 v[4:5], off
	v_lshl_add_u64 v[4:5], v[0:1], 0, s[14:15]
	s_add_i32 m0, s5, -16
	v_readfirstlane_b32 s5, v204
	global_load_lds_dwordx4 v[4:5], off
	v_lshl_add_u64 v[4:5], v[2:3], 0, s[14:15]
	s_add_i32 m0, s5, -16
	v_readfirstlane_b32 s5, v205
	global_load_lds_dwordx4 v[4:5], off
	v_lshl_add_u64 v[0:1], v[0:1], 0, s[20:21]
	s_add_i32 m0, s5, -16
	v_readfirstlane_b32 s5, v206
	global_load_lds_dwordx4 v[0:1], off
	v_lshl_add_u64 v[0:1], v[2:3], 0, s[20:21]
	s_add_i32 m0, s5, -16
	s_and_b32 s4, s35, 0x700
	global_load_lds_dwordx4 v[0:1], off
	s_lshl_b32 s5, s36, 11
	s_or_b32 s4, s4, s5
	v_add_u32_e32 v0, s4, v187
	s_lshl_b32 s4, s43, 14
	v_subrev_u32_e32 v0, s4, v0
	v_ashrrev_i32_e32 v1, 31, v0
	s_lshl_b32 s4, s43, 10
	v_lshlrev_b64 v[0:1], 12, v[0:1]
	s_or_b32 s4, s33, s4
	v_lshl_add_u64 v[128:129], v[158:159], 0, v[0:1]
	v_add_u32_e32 v0, s4, v187
	v_ashrrev_i32_e32 v1, 31, v0
	v_lshlrev_b64 v[0:1], 12, v[0:1]
	v_lshl_add_u64 v[130:131], v[160:161], 0, v[0:1]
	s_mov_b64 s[4:5], 0
	s_mov_b32 s43, 0
	v_mov_b32_e32 v0, 0
	v_mov_b32_e32 v1, v145
	v_mov_b32_e32 v2, v145
	v_mov_b32_e32 v3, v145
	v_mov_b32_e32 v4, v145
	v_mov_b32_e32 v5, v145
	v_mov_b32_e32 v6, v145
	v_mov_b32_e32 v7, v145
	s_waitcnt vmcnt(0)
	v_mov_b32_e32 v8, v145
	v_mov_b32_e32 v9, v145
	v_mov_b32_e32 v10, v145
	v_mov_b32_e32 v11, v145
	v_mov_b32_e32 v12, v145
	v_mov_b32_e32 v13, v145
	v_mov_b32_e32 v14, v145
	v_mov_b32_e32 v15, v145
	v_mov_b32_e32 v16, 0
	v_mov_b32_e32 v17, v145
	v_mov_b32_e32 v18, v145
	v_mov_b32_e32 v19, v145
	v_mov_b32_e32 v20, v145
	v_mov_b32_e32 v21, v145
	v_mov_b32_e32 v22, v145
	v_mov_b32_e32 v23, v145
	v_mov_b32_e32 v24, v145
	v_mov_b32_e32 v25, v145
	v_mov_b32_e32 v26, v145
	v_mov_b32_e32 v27, v145
	v_mov_b32_e32 v28, v145
	v_mov_b32_e32 v29, v145
	v_mov_b32_e32 v30, v145
	v_mov_b32_e32 v31, v145
	v_mov_b32_e32 v32, 0
	v_mov_b32_e32 v33, v145
	v_mov_b32_e32 v34, v145
	v_mov_b32_e32 v35, v145
	v_mov_b32_e32 v36, v145
	v_mov_b32_e32 v37, v145
	v_mov_b32_e32 v38, v145
	v_mov_b32_e32 v39, v145
	v_mov_b32_e32 v40, v145
	v_mov_b32_e32 v41, v145
	v_mov_b32_e32 v42, v145
	v_mov_b32_e32 v43, v145
	v_mov_b32_e32 v44, v145
	v_mov_b32_e32 v45, v145
	v_mov_b32_e32 v46, v145
	v_mov_b32_e32 v47, v145
	v_mov_b32_e32 v48, 0
	v_mov_b32_e32 v49, v145
	v_mov_b32_e32 v50, v145
	v_mov_b32_e32 v51, v145
	v_mov_b32_e32 v52, v145
	v_mov_b32_e32 v53, v145
	v_mov_b32_e32 v54, v145
	v_mov_b32_e32 v55, v145
	v_mov_b32_e32 v56, v145
	v_mov_b32_e32 v57, v145
	v_mov_b32_e32 v58, v145
	v_mov_b32_e32 v59, v145
	v_mov_b32_e32 v60, v145
	v_mov_b32_e32 v61, v145
	v_mov_b32_e32 v62, v145
	v_mov_b32_e32 v63, v145
	v_mov_b32_e32 v64, 0
	v_mov_b32_e32 v65, v145
	v_mov_b32_e32 v66, v145
	v_mov_b32_e32 v67, v145
	v_mov_b32_e32 v68, v145
	v_mov_b32_e32 v69, v145
	v_mov_b32_e32 v70, v145
	v_mov_b32_e32 v71, v145
	v_mov_b32_e32 v72, v145
	v_mov_b32_e32 v73, v145
	v_mov_b32_e32 v74, v145
	v_mov_b32_e32 v75, v145
	v_mov_b32_e32 v76, v145
	v_mov_b32_e32 v77, v145
	v_mov_b32_e32 v78, v145
	v_mov_b32_e32 v79, v145
	v_mov_b32_e32 v80, 0
	v_mov_b32_e32 v81, v145
	v_mov_b32_e32 v82, v145
	v_mov_b32_e32 v83, v145
	v_mov_b32_e32 v84, v145
	v_mov_b32_e32 v85, v145
	v_mov_b32_e32 v86, v145
	v_mov_b32_e32 v87, v145
	v_mov_b32_e32 v88, v145
	v_mov_b32_e32 v89, v145
	v_mov_b32_e32 v90, v145
	v_mov_b32_e32 v91, v145
	v_mov_b32_e32 v92, v145
	v_mov_b32_e32 v93, v145
	v_mov_b32_e32 v94, v145
	v_mov_b32_e32 v95, v145
	v_mov_b32_e32 v96, 0
	v_mov_b32_e32 v97, v145
	v_mov_b32_e32 v98, v145
	v_mov_b32_e32 v99, v145
	v_mov_b32_e32 v100, v145
	v_mov_b32_e32 v101, v145
	v_mov_b32_e32 v102, v145
	v_mov_b32_e32 v103, v145
	v_mov_b32_e32 v104, v145
	v_mov_b32_e32 v105, v145
	v_mov_b32_e32 v106, v145
	v_mov_b32_e32 v107, v145
	v_mov_b32_e32 v108, v145
	v_mov_b32_e32 v109, v145
	v_mov_b32_e32 v110, v145
	v_mov_b32_e32 v111, v145
	v_mov_b32_e32 v112, 0
	v_mov_b32_e32 v113, v145
	v_mov_b32_e32 v114, v145
	v_mov_b32_e32 v115, v145
	v_mov_b32_e32 v116, v145
	v_mov_b32_e32 v117, v145
	v_mov_b32_e32 v118, v145
	v_mov_b32_e32 v119, v145
	v_mov_b32_e32 v120, v145
	v_mov_b32_e32 v121, v145
	v_mov_b32_e32 v122, v145
	v_mov_b32_e32 v123, v145
	v_mov_b32_e32 v124, v145
	v_mov_b32_e32 v125, v145
	v_mov_b32_e32 v126, v145
	v_mov_b32_e32 v127, v145
	s_waitcnt lgkmcnt(0)
	s_barrier
	v_readfirstlane_b32 s48, v188
	s_sub_u32 s48, s48, 16
	s_mov_b32 s49, 0
	s_mov_b32 s50, 0x8000
	s_mov_b32 s52, 0x10000
	v_and_b32_e32 v140, 63, v186
	v_and_b32_e32 v141, 15, v140
	v_lshrrev_b32_e32 v136, 4, v140
	v_bfe_u32 v137, v140, 1, 3
	v_xor_b32_e32 v132, v136, v137
	v_or_b32_e32 v136, 4, v136
	v_xor_b32_e32 v133, v136, v137
	v_lshlrev_b32_e32 v132, 4, v132
	v_lshlrev_b32_e32 v133, 4, v133
	v_lshl_add_u32 v132, v141, 7, v132
	v_lshl_add_u32 v133, v141, 7, v133
	v_bfe_u32 v136, v186, 6, 2
	v_lshl_add_u32 v134, v136, 13, v132
	v_lshl_add_u32 v135, v136, 13, v133
	v_lshrrev_b32_e32 v136, 8, v186
	v_lshl_add_u32 v132, v136, 14, v132
	v_lshl_add_u32 v133, v136, 14, v133
	v_readfirstlane_b32 s56, v128
	v_readfirstlane_b32 s57, v129
	s_and_b32 s53, s48, 0x400
	s_lshr_b32 s53, s53, 4
	s_sub_u32 s56, s56, s53
	s_subb_u32 s57, s57, 0
	v_subrev_u32_e32 v138, s56, v128
	s_add_u32 s62, s56, s28
	s_addc_u32 s63, s57, s29
	s_add_u32 s60, s56, s26
	s_addc_u32 s61, s57, s27
	s_add_u32 s58, s56, s24
	s_addc_u32 s59, s57, s25
	s_add_u32 s56, s56, s22
	s_addc_u32 s57, s57, s23
	v_readfirstlane_b32 s64, v130
	v_readfirstlane_b32 s65, v131
	s_and_b32 s53, s48, 0x400
	s_lshr_b32 s53, s53, 4
	s_sub_u32 s64, s64, s53
	s_subb_u32 s65, s65, 0
	v_subrev_u32_e32 v139, s64, v130
	s_add_u32 s70, s64, s28
	s_addc_u32 s71, s65, s29
	s_add_u32 s68, s64, s26
	s_addc_u32 s69, s65, s27
	s_add_u32 s66, s64, s24
	s_addc_u32 s67, s65, s25
	s_add_u32 s64, s64, s22
	s_addc_u32 s65, s65, s23
	s_add_u32 m0, s52, s48
	s_nop 0
	global_load_lds_dwordx4 v138, s[56:57]
	s_add_u32 s56, s56, 0x80
	s_addc_u32 s57, s57, 0
	s_add_u32 s53, s52, s48
	s_add_u32 m0, s53, 0x2000
	s_nop 0
	global_load_lds_dwordx4 v138, s[58:59]
	s_add_u32 s58, s58, 0x80
	s_addc_u32 s59, s59, 0
	s_add_u32 s53, s52, s48
	s_add_u32 m0, s53, 0x4000
	s_nop 0
	global_load_lds_dwordx4 v138, s[60:61]
	s_add_u32 s60, s60, 0x80
	s_addc_u32 s61, s61, 0
	s_add_u32 s53, s52, s48
	s_add_u32 m0, s53, 0x6000
	s_nop 0
	global_load_lds_dwordx4 v138, s[62:63]
	s_add_u32 s62, s62, 0x80
	s_addc_u32 s63, s63, 0
	v_add_u32_e32 v137, s50, v134
	v_add_u32_e32 v136, s49, v132
	ds_read_b128 v[164:167], v137
	ds_read_b128 v[168:171], v137 offset:2048
	ds_read_b128 v[172:175], v137 offset:4096
	ds_read_b128 v[176:179], v137 offset:6144
	ds_read_b128 v[224:227], v136
	ds_read_b128 v[228:231], v136 offset:2048
	ds_read_b128 v[232:235], v136 offset:4096
	ds_read_b128 v[236:239], v136 offset:6144
	.p2align 6

.LBB0_164:
	s_ashr_i32 s33, s30, 2
	s_and_b32 s33, s33, -8
	s_or_b32 s33, s33, s3
	s_ashr_i32 s37, s33, 31
	s_lshr_b32 s37, s37, 29
	s_add_i32 s37, s33, s37
	s_ashr_i32 s39, s37, 3
	s_and_b32 s37, s37, 0x1ffff8
	s_sub_i32 s37, s33, s37
	s_lshl_b32 s38, s30, 8
	s_lshl_b32 s37, s37, 11
	s_and_b32 s38, s38, 0x700
	s_or_b32 s37, s37, s38
	s_lshl_b32 s38, s30, 5
	s_lshl_b32 s40, s39, 10
	s_and_b32 s38, s38, 0x300
	v_add_u32_e32 v0, s37, v149
	s_or_b32 s38, s40, s38
	v_ashrrev_i32_e32 v1, 31, v0
	v_add_u32_e32 v2, s38, v149
	v_lshlrev_b64 v[0:1], 12, v[0:1]
	v_ashrrev_i32_e32 v3, 31, v2
	v_readfirstlane_b32 s41, v150
	v_lshl_add_u64 v[0:1], v[130:131], 0, v[0:1]
	v_lshlrev_b64 v[2:3], 12, v[2:3]
	s_add_i32 m0, s41, -16
	v_readfirstlane_b32 s41, v128
	v_lshl_add_u64 v[2:3], v[132:133], 0, v[2:3]
	global_load_lds_dwordx4 v[0:1], off
	s_add_i32 m0, s41, -16
	v_readfirstlane_b32 s41, v160
	global_load_lds_dwordx4 v[2:3], off
	v_lshl_add_u64 v[4:5], v[0:1], 0, s[12:13]
	s_add_i32 m0, s41, -16
	v_readfirstlane_b32 s41, v161
	global_load_lds_dwordx4 v[4:5], off
	v_lshl_add_u64 v[4:5], v[2:3], 0, s[12:13]
	s_add_i32 m0, s41, -16
	v_readfirstlane_b32 s41, v162
	global_load_lds_dwordx4 v[4:5], off
	v_lshl_add_u64 v[4:5], v[0:1], 0, s[14:15]
	s_add_i32 m0, s41, -16
	v_readfirstlane_b32 s41, v163
	global_load_lds_dwordx4 v[4:5], off
	v_lshl_add_u64 v[4:5], v[2:3], 0, s[14:15]
	s_add_i32 m0, s41, -16
	v_readfirstlane_b32 s41, v164
	global_load_lds_dwordx4 v[4:5], off
	v_lshl_add_u64 v[0:1], v[0:1], 0, s[16:17]
	s_add_i32 m0, s41, -16
	v_readfirstlane_b32 s41, v165
	global_load_lds_dwordx4 v[0:1], off
	v_lshl_add_u64 v[0:1], v[2:3], 0, s[16:17]
	s_add_i32 m0, s41, -16
	s_and_b32 s28, s31, 0x700
	global_load_lds_dwordx4 v[0:1], off
	s_lshl_b32 s33, s33, 11
	s_or_b32 s28, s28, s33
	v_add_u32_e32 v0, s28, v149
	s_lshl_b32 s28, s39, 14
	v_subrev_u32_e32 v0, s28, v0
	s_and_b32 s29, s35, 0x300
	v_ashrrev_i32_e32 v1, 31, v0
	v_lshlrev_b64 v[0:1], 12, v[0:1]
	s_or_b32 s28, s29, s40
	v_lshl_add_u64 v[138:139], v[134:135], 0, v[0:1]
	v_add_u32_e32 v0, s28, v149
	v_ashrrev_i32_e32 v1, 31, v0
	v_lshlrev_b64 v[0:1], 12, v[0:1]
	v_lshl_add_u64 v[140:141], v[136:137], 0, v[0:1]
	s_mov_b32 s39, 0
	s_mov_b64 s[28:29], 0
	v_mov_b32_e32 v0, 0
	v_mov_b32_e32 v1, v129
	v_mov_b32_e32 v2, v129
	v_mov_b32_e32 v3, v129
	v_mov_b32_e32 v4, v129
	v_mov_b32_e32 v5, v129
	v_mov_b32_e32 v6, v129
	v_mov_b32_e32 v7, v129
	v_mov_b32_e32 v8, v129
	v_mov_b32_e32 v9, v129
	v_mov_b32_e32 v10, v129
	v_mov_b32_e32 v11, v129
	v_mov_b32_e32 v12, v129
	v_mov_b32_e32 v13, v129
	v_mov_b32_e32 v14, v129
	v_mov_b32_e32 v15, v129
	v_mov_b32_e32 v16, 0
	v_mov_b32_e32 v17, v129
	v_mov_b32_e32 v18, v129
	v_mov_b32_e32 v19, v129
	v_mov_b32_e32 v20, v129
	v_mov_b32_e32 v21, v129
	v_mov_b32_e32 v22, v129
	v_mov_b32_e32 v23, v129
	v_mov_b32_e32 v24, v129
	v_mov_b32_e32 v25, v129
	v_mov_b32_e32 v26, v129
	v_mov_b32_e32 v27, v129
	v_mov_b32_e32 v28, v129
	v_mov_b32_e32 v29, v129
	v_mov_b32_e32 v30, v129
	v_mov_b32_e32 v31, v129
	v_mov_b32_e32 v32, 0
	v_mov_b32_e32 v33, v129
	v_mov_b32_e32 v34, v129
	v_mov_b32_e32 v35, v129
	v_mov_b32_e32 v36, v129
	v_mov_b32_e32 v37, v129
	v_mov_b32_e32 v38, v129
	v_mov_b32_e32 v39, v129
	v_mov_b32_e32 v40, v129
	v_mov_b32_e32 v41, v129
	v_mov_b32_e32 v42, v129
	v_mov_b32_e32 v43, v129
	v_mov_b32_e32 v44, v129
	v_mov_b32_e32 v45, v129
	v_mov_b32_e32 v46, v129
	v_mov_b32_e32 v47, v129
	v_mov_b32_e32 v48, 0
	v_mov_b32_e32 v49, v129
	v_mov_b32_e32 v50, v129
	v_mov_b32_e32 v51, v129
	v_mov_b32_e32 v52, v129
	v_mov_b32_e32 v53, v129
	v_mov_b32_e32 v54, v129
	v_mov_b32_e32 v55, v129
	v_mov_b32_e32 v56, v129
	v_mov_b32_e32 v57, v129
	v_mov_b32_e32 v58, v129
	v_mov_b32_e32 v59, v129
	v_mov_b32_e32 v60, v129
	v_mov_b32_e32 v61, v129
	v_mov_b32_e32 v62, v129
	v_mov_b32_e32 v63, v129
	v_mov_b32_e32 v64, 0
	v_mov_b32_e32 v65, v129
	v_mov_b32_e32 v66, v129
	v_mov_b32_e32 v67, v129
	v_mov_b32_e32 v68, v129
	v_mov_b32_e32 v69, v129
	v_mov_b32_e32 v70, v129
	v_mov_b32_e32 v71, v129
	v_mov_b32_e32 v72, v129
	v_mov_b32_e32 v73, v129
	v_mov_b32_e32 v74, v129
	v_mov_b32_e32 v75, v129
	v_mov_b32_e32 v76, v129
	v_mov_b32_e32 v77, v129
	v_mov_b32_e32 v78, v129
	v_mov_b32_e32 v79, v129
	v_mov_b32_e32 v80, 0
	v_mov_b32_e32 v81, v129
	v_mov_b32_e32 v82, v129
	v_mov_b32_e32 v83, v129
	v_mov_b32_e32 v84, v129
	v_mov_b32_e32 v85, v129
	v_mov_b32_e32 v86, v129
	v_mov_b32_e32 v87, v129
	v_mov_b32_e32 v88, v129
	v_mov_b32_e32 v89, v129
	v_mov_b32_e32 v90, v129
	v_mov_b32_e32 v91, v129
	v_mov_b32_e32 v92, v129
	v_mov_b32_e32 v93, v129
	v_mov_b32_e32 v94, v129
	v_mov_b32_e32 v95, v129
	v_mov_b32_e32 v96, 0
	v_mov_b32_e32 v97, v129
	v_mov_b32_e32 v98, v129
	v_mov_b32_e32 v99, v129
	v_mov_b32_e32 v100, v129
	v_mov_b32_e32 v101, v129
	v_mov_b32_e32 v102, v129
	v_mov_b32_e32 v103, v129
	v_mov_b32_e32 v104, v129
	v_mov_b32_e32 v105, v129
	v_mov_b32_e32 v106, v129
	v_mov_b32_e32 v107, v129
	v_mov_b32_e32 v108, v129
	v_mov_b32_e32 v109, v129
	v_mov_b32_e32 v110, v129
	v_mov_b32_e32 v111, v129
	v_mov_b32_e32 v112, 0
	v_mov_b32_e32 v113, v129
	v_mov_b32_e32 v114, v129
	v_mov_b32_e32 v115, v129
	v_mov_b32_e32 v116, v129
	v_mov_b32_e32 v117, v129
	v_mov_b32_e32 v118, v129
	v_mov_b32_e32 v119, v129
	v_mov_b32_e32 v120, v129
	v_mov_b32_e32 v121, v129
	v_mov_b32_e32 v122, v129
	v_mov_b32_e32 v123, v129
	v_mov_b32_e32 v124, v129
	v_mov_b32_e32 v125, v129
	v_mov_b32_e32 v126, v129
	v_mov_b32_e32 v127, v129
	s_waitcnt vmcnt(0) lgkmcnt(0)
	s_barrier
	v_readfirstlane_b32 s48, v150
	s_sub_u32 s48, s48, 16
	s_mov_b32 s49, 0
	s_mov_b32 s50, 0x8000
	s_mov_b32 s52, 0x10000
	v_and_b32_e32 v170, 63, v186
	v_and_b32_e32 v171, 15, v170
	v_lshrrev_b32_e32 v166, 4, v170
	v_bfe_u32 v167, v170, 1, 3
	v_xor_b32_e32 v142, v166, v167
	v_or_b32_e32 v166, 4, v166
	v_xor_b32_e32 v143, v166, v167
	v_lshlrev_b32_e32 v142, 4, v142
	v_lshlrev_b32_e32 v143, 4, v143
	v_lshl_add_u32 v142, v171, 7, v142
	v_lshl_add_u32 v143, v171, 7, v143
	v_bfe_u32 v166, v186, 6, 2
	v_lshl_add_u32 v144, v166, 13, v142
	v_lshl_add_u32 v145, v166, 13, v143
	v_lshrrev_b32_e32 v166, 8, v186
	v_lshl_add_u32 v142, v166, 14, v142
	v_lshl_add_u32 v143, v166, 14, v143
	v_readfirstlane_b32 s56, v138
	v_readfirstlane_b32 s57, v139
	s_and_b32 s53, s48, 0x400
	s_lshr_b32 s53, s53, 4
	s_sub_u32 s56, s56, s53
	s_subb_u32 s57, s57, 0
	v_subrev_u32_e32 v168, s56, v138
	s_add_u32 s62, s56, s24
	s_addc_u32 s63, s57, s25
	s_add_u32 s60, s56, s22
	s_addc_u32 s61, s57, s23
	s_add_u32 s58, s56, s20
	s_addc_u32 s59, s57, s21
	s_add_u32 s56, s56, s18
	s_addc_u32 s57, s57, s19
	v_readfirstlane_b32 s64, v140
	v_readfirstlane_b32 s65, v141
	s_and_b32 s53, s48, 0x400
	s_lshr_b32 s53, s53, 4
	s_sub_u32 s64, s64, s53
	s_subb_u32 s65, s65, 0
	v_subrev_u32_e32 v169, s64, v140
	s_add_u32 s70, s64, s24
	s_addc_u32 s71, s65, s25
	s_add_u32 s68, s64, s22
	s_addc_u32 s69, s65, s23
	s_add_u32 s66, s64, s20
	s_addc_u32 s67, s65, s21
	s_add_u32 s64, s64, s18
	s_addc_u32 s65, s65, s19
	s_add_u32 m0, s52, s48
	s_nop 0
	global_load_lds_dwordx4 v168, s[56:57]
	s_add_u32 s56, s56, 0x80
	s_addc_u32 s57, s57, 0
	s_add_u32 s53, s52, s48
	s_add_u32 m0, s53, 0x2000
	s_nop 0
	global_load_lds_dwordx4 v168, s[58:59]
	s_add_u32 s58, s58, 0x80
	s_addc_u32 s59, s59, 0
	s_add_u32 s53, s52, s48
	s_add_u32 m0, s53, 0x4000
	s_nop 0
	global_load_lds_dwordx4 v168, s[60:61]
	s_add_u32 s60, s60, 0x80
	s_addc_u32 s61, s61, 0
	s_add_u32 s53, s52, s48
	s_add_u32 m0, s53, 0x6000
	s_nop 0
	global_load_lds_dwordx4 v168, s[62:63]
	s_add_u32 s62, s62, 0x80
	s_addc_u32 s63, s63, 0
	v_add_u32_e32 v167, s50, v144
	v_add_u32_e32 v166, s49, v142
	ds_read_b128 v[188:191], v167
	ds_read_b128 v[192:195], v167 offset:2048
	ds_read_b128 v[196:199], v167 offset:4096
	ds_read_b128 v[200:203], v167 offset:6144
	ds_read_b128 v[220:223], v166
	ds_read_b128 v[224:227], v166 offset:2048
	ds_read_b128 v[228:231], v166 offset:4096
	ds_read_b128 v[232:235], v166 offset:6144
	.p2align 6

.LBB0_198:
	s_ashr_i32 s27, s30, 2
	s_and_b32 s27, s27, -8
	s_or_b32 s33, s27, s3
	s_ashr_i32 s27, s33, 31
	s_lshr_b32 s27, s27, 29
	s_add_i32 s27, s33, s27
	s_ashr_i32 s46, s27, 3
	s_bfe_u32 s26, s30, 0x20003
	s_and_b32 s27, s27, 0x1ffff8
	s_lshl_b32 s47, s46, 2
	s_lshl_b32 s29, s26, 8
	s_sub_i32 s27, s33, s27
	s_or_b32 s26, s47, s26
	s_lshl_b32 s47, s30, 8
	s_lshl_b32 s27, s27, 11
	s_and_b32 s47, s47, 0x700
	s_or_b32 s27, s27, s47
	v_add_u32_e32 v0, s27, v142
	v_ashrrev_i32_e32 v1, 31, v0
	v_lshl_add_u32 v2, s26, 8, v142
	v_lshlrev_b64 v[0:1], 12, v[0:1]
	v_ashrrev_i32_e32 v3, 31, v2
	v_readfirstlane_b32 s47, v143
	v_add_u32_e32 v4, 0x8000, v143
	v_lshl_add_u64 v[0:1], v[130:131], 0, v[0:1]
	v_lshlrev_b64 v[2:3], 12, v[2:3]
	s_add_i32 m0, s47, -16
	v_readfirstlane_b32 s47, v4
	v_add_u32_e32 v6, 0x2000, v143
	v_lshl_add_u64 v[2:3], v[132:133], 0, v[2:3]
	global_load_lds_dwordx4 v[0:1], off
	s_add_i32 m0, s47, -16
	v_readfirstlane_b32 s47, v6
	v_add_u32_e32 v6, 0xa000, v143
	global_load_lds_dwordx4 v[2:3], off
	v_lshl_add_u64 v[4:5], v[0:1], 0, s[12:13]
	s_add_i32 m0, s47, -16
	v_readfirstlane_b32 s47, v6
	v_add_u32_e32 v6, 0x4000, v143
	global_load_lds_dwordx4 v[4:5], off
	v_lshl_add_u64 v[4:5], v[2:3], 0, s[12:13]
	s_add_i32 m0, s47, -16
	v_readfirstlane_b32 s47, v6
	v_add_u32_e32 v6, 0xc000, v143
	global_load_lds_dwordx4 v[4:5], off
	v_lshl_add_u64 v[4:5], v[0:1], 0, s[14:15]
	s_add_i32 m0, s47, -16
	v_readfirstlane_b32 s47, v6
	global_load_lds_dwordx4 v[4:5], off
	v_lshl_add_u64 v[4:5], v[2:3], 0, s[14:15]
	s_add_i32 m0, s47, -16
	v_lshl_add_u64 v[0:1], v[0:1], 0, s[16:17]
	global_load_lds_dwordx4 v[4:5], off
	v_add_u32_e32 v4, 0x6000, v143
	s_and_b32 s28, s34, 0x700
	v_readfirstlane_b32 s47, v4
	s_add_i32 m0, s47, -16
	s_lshl_b32 s33, s33, 11
	global_load_lds_dwordx4 v[0:1], off
	v_lshl_add_u64 v[0:1], v[2:3], 0, s[16:17]
	v_add_u32_e32 v2, 0xe000, v143
	s_or_b32 s28, s28, s33
	v_readfirstlane_b32 s47, v2
	s_add_i32 m0, s47, -16
	v_mov_b32_e32 v2, v129
	global_load_lds_dwordx4 v[0:1], off
	v_add_u32_e32 v0, s28, v142
	s_lshl_b32 s28, s46, 14
	v_subrev_u32_e32 v0, s28, v0
	v_ashrrev_i32_e32 v1, 31, v0
	s_lshl_b32 s28, s46, 10
	v_lshlrev_b64 v[0:1], 12, v[0:1]
	s_or_b32 s28, s29, s28
	v_lshl_add_u64 v[138:139], v[134:135], 0, v[0:1]
	v_add_u32_e32 v0, s28, v142
	v_ashrrev_i32_e32 v1, 31, v0
	v_lshlrev_b64 v[0:1], 12, v[0:1]
	v_lshl_add_u64 v[140:141], v[136:137], 0, v[0:1]
	s_mov_b64 s[28:29], 0
	s_mov_b32 s46, 0
	v_mov_b32_e32 v0, 0
	v_mov_b32_e32 v1, v129
	v_mov_b32_e32 v3, v129
	v_mov_b32_e32 v4, v129
	v_mov_b32_e32 v5, v129
	v_mov_b32_e32 v6, v129
	v_mov_b32_e32 v7, v129
	v_mov_b32_e32 v8, v129
	v_mov_b32_e32 v9, v129
	v_mov_b32_e32 v10, v129
	v_mov_b32_e32 v11, v129
	v_mov_b32_e32 v12, v129
	v_mov_b32_e32 v13, v129
	v_mov_b32_e32 v14, v129
	v_mov_b32_e32 v15, v129
	v_mov_b32_e32 v16, 0
	v_mov_b32_e32 v17, v129
	v_mov_b32_e32 v18, v129
	v_mov_b32_e32 v19, v129
	v_mov_b32_e32 v20, v129
	v_mov_b32_e32 v21, v129
	v_mov_b32_e32 v22, v129
	v_mov_b32_e32 v23, v129
	v_mov_b32_e32 v24, v129
	v_mov_b32_e32 v25, v129
	v_mov_b32_e32 v26, v129
	v_mov_b32_e32 v27, v129
	v_mov_b32_e32 v28, v129
	v_mov_b32_e32 v29, v129
	v_mov_b32_e32 v30, v129
	v_mov_b32_e32 v31, v129
	v_mov_b32_e32 v32, 0
	v_mov_b32_e32 v33, v129
	v_mov_b32_e32 v34, v129
	v_mov_b32_e32 v35, v129
	v_mov_b32_e32 v36, v129
	v_mov_b32_e32 v37, v129
	v_mov_b32_e32 v38, v129
	v_mov_b32_e32 v39, v129
	v_mov_b32_e32 v40, v129
	v_mov_b32_e32 v41, v129
	v_mov_b32_e32 v42, v129
	v_mov_b32_e32 v43, v129
	v_mov_b32_e32 v44, v129
	v_mov_b32_e32 v45, v129
	v_mov_b32_e32 v46, v129
	v_mov_b32_e32 v47, v129
	v_mov_b32_e32 v48, 0
	v_mov_b32_e32 v49, v129
	v_mov_b32_e32 v50, v129
	v_mov_b32_e32 v51, v129
	v_mov_b32_e32 v52, v129
	v_mov_b32_e32 v53, v129
	v_mov_b32_e32 v54, v129
	v_mov_b32_e32 v55, v129
	v_mov_b32_e32 v56, v129
	v_mov_b32_e32 v57, v129
	v_mov_b32_e32 v58, v129
	v_mov_b32_e32 v59, v129
	v_mov_b32_e32 v60, v129
	v_mov_b32_e32 v61, v129
	v_mov_b32_e32 v62, v129
	v_mov_b32_e32 v63, v129
	v_mov_b32_e32 v64, 0
	v_mov_b32_e32 v65, v129
	v_mov_b32_e32 v66, v129
	v_mov_b32_e32 v67, v129
	v_mov_b32_e32 v68, v129
	v_mov_b32_e32 v69, v129
	v_mov_b32_e32 v70, v129
	v_mov_b32_e32 v71, v129
	v_mov_b32_e32 v72, v129
	v_mov_b32_e32 v73, v129
	v_mov_b32_e32 v74, v129
	v_mov_b32_e32 v75, v129
	v_mov_b32_e32 v76, v129
	v_mov_b32_e32 v77, v129
	v_mov_b32_e32 v78, v129
	v_mov_b32_e32 v79, v129
	v_mov_b32_e32 v80, 0
	v_mov_b32_e32 v81, v129
	v_mov_b32_e32 v82, v129
	v_mov_b32_e32 v83, v129
	v_mov_b32_e32 v84, v129
	v_mov_b32_e32 v85, v129
	v_mov_b32_e32 v86, v129
	v_mov_b32_e32 v87, v129
	v_mov_b32_e32 v88, v129
	v_mov_b32_e32 v89, v129
	v_mov_b32_e32 v90, v129
	v_mov_b32_e32 v91, v129
	v_mov_b32_e32 v92, v129
	v_mov_b32_e32 v93, v129
	v_mov_b32_e32 v94, v129
	v_mov_b32_e32 v95, v129
	v_mov_b32_e32 v96, 0
	v_mov_b32_e32 v97, v129
	v_mov_b32_e32 v98, v129
	v_mov_b32_e32 v99, v129
	v_mov_b32_e32 v100, v129
	v_mov_b32_e32 v101, v129
	v_mov_b32_e32 v102, v129
	v_mov_b32_e32 v103, v129
	v_mov_b32_e32 v104, v129
	v_mov_b32_e32 v105, v129
	v_mov_b32_e32 v106, v129
	v_mov_b32_e32 v107, v129
	v_mov_b32_e32 v108, v129
	v_mov_b32_e32 v109, v129
	v_mov_b32_e32 v110, v129
	v_mov_b32_e32 v111, v129
	v_mov_b32_e32 v112, 0
	v_mov_b32_e32 v113, v129
	v_mov_b32_e32 v114, v129
	v_mov_b32_e32 v115, v129
	v_mov_b32_e32 v116, v129
	v_mov_b32_e32 v117, v129
	v_mov_b32_e32 v118, v129
	v_mov_b32_e32 v119, v129
	v_mov_b32_e32 v120, v129
	v_mov_b32_e32 v121, v129
	v_mov_b32_e32 v122, v129
	v_mov_b32_e32 v123, v129
	v_mov_b32_e32 v124, v129
	v_mov_b32_e32 v125, v129
	v_mov_b32_e32 v126, v129
	v_mov_b32_e32 v127, v129
	s_waitcnt vmcnt(0) lgkmcnt(0)
	s_barrier
	v_readfirstlane_b32 s48, v143
	s_sub_u32 s48, s48, 16
	s_mov_b32 s49, 0
	s_mov_b32 s50, 0x8000
	s_mov_b32 s52, 0x10000
	v_and_b32_e32 v249, 63, v186
	v_and_b32_e32 v250, 15, v249
	v_lshrrev_b32_e32 v245, 4, v249
	v_bfe_u32 v246, v249, 1, 3
	v_xor_b32_e32 v240, v245, v246
	v_or_b32_e32 v245, 4, v245
	v_xor_b32_e32 v241, v245, v246
	v_lshlrev_b32_e32 v240, 4, v240
	v_lshlrev_b32_e32 v241, 4, v241
	v_lshl_add_u32 v240, v250, 7, v240
	v_lshl_add_u32 v241, v250, 7, v241
	v_bfe_u32 v245, v186, 6, 2
	v_lshl_add_u32 v243, v245, 13, v240
	v_lshl_add_u32 v244, v245, 13, v241
	v_lshrrev_b32_e32 v245, 8, v186
	v_lshl_add_u32 v240, v245, 14, v240
	v_lshl_add_u32 v241, v245, 14, v241
	v_readfirstlane_b32 s56, v138
	v_readfirstlane_b32 s57, v139
	s_and_b32 s53, s48, 0x400
	s_lshr_b32 s53, s53, 4
	s_sub_u32 s56, s56, s53
	s_subb_u32 s57, s57, 0
	v_subrev_u32_e32 v247, s56, v138
	s_add_u32 s62, s56, s24
	s_addc_u32 s63, s57, s25
	s_add_u32 s60, s56, s22
	s_addc_u32 s61, s57, s23
	s_add_u32 s58, s56, s20
	s_addc_u32 s59, s57, s21
	s_add_u32 s56, s56, s18
	s_addc_u32 s57, s57, s19
	v_readfirstlane_b32 s64, v140
	v_readfirstlane_b32 s65, v141
	s_and_b32 s53, s48, 0x400
	s_lshr_b32 s53, s53, 4
	s_sub_u32 s64, s64, s53
	s_subb_u32 s65, s65, 0
	v_subrev_u32_e32 v248, s64, v140
	s_add_u32 s70, s64, s24
	s_addc_u32 s71, s65, s25
	s_add_u32 s68, s64, s22
	s_addc_u32 s69, s65, s23
	s_add_u32 s66, s64, s20
	s_addc_u32 s67, s65, s21
	s_add_u32 s64, s64, s18
	s_addc_u32 s65, s65, s19
	s_add_u32 m0, s52, s48
	s_nop 0
	global_load_lds_dwordx4 v247, s[56:57]
	s_add_u32 s56, s56, 0x80
	s_addc_u32 s57, s57, 0
	s_add_u32 s53, s52, s48
	s_add_u32 m0, s53, 0x2000
	s_nop 0
	global_load_lds_dwordx4 v247, s[58:59]
	s_add_u32 s58, s58, 0x80
	s_addc_u32 s59, s59, 0
	s_add_u32 s53, s52, s48
	s_add_u32 m0, s53, 0x4000
	s_nop 0
	global_load_lds_dwordx4 v247, s[60:61]
	s_add_u32 s60, s60, 0x80
	s_addc_u32 s61, s61, 0
	s_add_u32 s53, s52, s48
	s_add_u32 m0, s53, 0x6000
	s_nop 0
	global_load_lds_dwordx4 v247, s[62:63]
	s_add_u32 s62, s62, 0x80
	s_addc_u32 s63, s63, 0
	v_add_u32_e32 v246, s50, v243
	v_add_u32_e32 v245, s49, v240
	ds_read_b128 v[192:195], v246
	ds_read_b128 v[196:199], v246 offset:2048
	ds_read_b128 v[200:203], v246 offset:4096
	ds_read_b128 v[204:207], v246 offset:6144
	ds_read_b128 v[224:227], v245
	ds_read_b128 v[228:231], v245 offset:2048
	ds_read_b128 v[232:235], v245 offset:4096
	ds_read_b128 v[236:239], v245 offset:6144
	.p2align 6

.Lex_chunk:
	s_movk_i32 s36, 0
	s_mul_i32 s37, s36, s5
	s_add_i32 s37, s37, s6
	s_min_u32 s37, s37, 0x3fff
	s_lshl_b32 s37, s37, 9
	s_add_u32 s82, s12, s37
	s_addc_u32 s83, s13, 0
	v_lshlrev_b32_e32 v219, 2, v228
	global_load_dword v96, v219, s[82:83]
	global_load_dword v97, v219, s[82:83] offset:256
	s_movk_i32 s36, 1
	s_mul_i32 s37, s36, s5
	s_add_i32 s37, s37, s6
	s_min_u32 s37, s37, 0x3fff
	s_lshl_b32 s37, s37, 9
	s_add_u32 s82, s12, s37
	s_addc_u32 s83, s13, 0
	v_lshlrev_b32_e32 v219, 2, v228
	global_load_dword v98, v219, s[82:83]
	global_load_dword v99, v219, s[82:83] offset:256
	s_movk_i32 s36, 2
	s_mul_i32 s37, s36, s5
	s_add_i32 s37, s37, s6
	s_min_u32 s37, s37, 0x3fff
	s_lshl_b32 s37, s37, 9
	s_add_u32 s82, s12, s37
	s_addc_u32 s83, s13, 0
	v_lshlrev_b32_e32 v219, 2, v228
	global_load_dword v100, v219, s[82:83]
	global_load_dword v101, v219, s[82:83] offset:256
	s_movk_i32 s36, 3
	s_mul_i32 s37, s36, s5
	s_add_i32 s37, s37, s6
	s_min_u32 s37, s37, 0x3fff
	s_lshl_b32 s37, s37, 9
	s_add_u32 s82, s12, s37
	s_addc_u32 s83, s13, 0
	v_lshlrev_b32_e32 v219, 2, v228
	global_load_dword v102, v219, s[82:83]
	global_load_dword v103, v219, s[82:83] offset:256
	s_movk_i32 s36, 4
	s_mul_i32 s37, s36, s5
	s_add_i32 s37, s37, s6
	s_min_u32 s37, s37, 0x3fff
	s_lshl_b32 s37, s37, 9
	s_add_u32 s82, s12, s37
	s_addc_u32 s83, s13, 0
	v_lshlrev_b32_e32 v219, 2, v228
	global_load_dword v104, v219, s[82:83]
	global_load_dword v105, v219, s[82:83] offset:256
	s_movk_i32 s36, 5
	s_mul_i32 s37, s36, s5
	s_add_i32 s37, s37, s6
	s_min_u32 s37, s37, 0x3fff
	s_lshl_b32 s37, s37, 9
	s_add_u32 s82, s12, s37
	s_addc_u32 s83, s13, 0
	v_lshlrev_b32_e32 v219, 2, v228
	global_load_dword v106, v219, s[82:83]
	global_load_dword v107, v219, s[82:83] offset:256
	s_movk_i32 s36, 6
	s_mul_i32 s37, s36, s5
	s_add_i32 s37, s37, s6
	s_min_u32 s37, s37, 0x3fff
	s_lshl_b32 s37, s37, 9
	s_add_u32 s82, s12, s37
	s_addc_u32 s83, s13, 0
	v_lshlrev_b32_e32 v219, 2, v228
	global_load_dword v108, v219, s[82:83]
	global_load_dword v109, v219, s[82:83] offset:256
	s_movk_i32 s36, 7
	s_mul_i32 s37, s36, s5
	s_add_i32 s37, s37, s6
	s_min_u32 s37, s37, 0x3fff
	s_lshl_b32 s37, s37, 9
	s_add_u32 s82, s12, s37
	s_addc_u32 s83, s13, 0
	v_lshlrev_b32_e32 v219, 2, v228
	global_load_dword v110, v219, s[82:83]
	global_load_dword v111, v219, s[82:83] offset:256
	s_waitcnt vmcnt(0)
	ds_write_b32 v230, v96 offset:0
	ds_write_b32 v230, v97 offset:256
	ds_write_b32 v230, v98 offset:512
	ds_write_b32 v230, v99 offset:768
	ds_write_b32 v230, v100 offset:1024
	ds_write_b32 v230, v101 offset:1280
	ds_write_b32 v230, v102 offset:1536
	ds_write_b32 v230, v103 offset:1792
	ds_write_b32 v230, v104 offset:2048
	ds_write_b32 v230, v105 offset:2304
	ds_write_b32 v230, v106 offset:2560
	ds_write_b32 v230, v107 offset:2816
	ds_write_b32 v230, v108 offset:3072
	ds_write_b32 v230, v109 offset:3328
	ds_write_b32 v230, v110 offset:3584
	ds_write_b32 v230, v111 offset:3840
	s_waitcnt lgkmcnt(0)
	v_lshrrev_b32_e32 v212, 3, v228
	v_lshl_add_u32 v234, v212, 9, v224
	s_lshr_b32 s34, s64, 13
	s_lshl_b32 s34, s34, 9
	s_add_i32 s34, s34, 0x10010
	v_lshl_add_u32 v235, v228, 3, s34
	v_add_u32_e32 v248, s34, v224
	s_mov_b32 s8, 0
	s_mov_b32 s7, 0
	s_mov_b32 s54, 0
	s_mov_b32 s53, 0
	s_mul_i32 s55, s53, s5
	s_add_i32 s55, s55, s6
	s_min_u32 s55, s55, 0x3fff
	s_and_b32 s34, s54, 7
	s_mul_i32 s34, s34, 0x300000
	s_cmp_lt_u32 s54, 8
	s_cselect_b32 s30, s16, s18
	s_cselect_b32 s31, s17, s19
	s_add_u32 s30, s30, s34
	s_addc_u32 s31, s31, 0
	s_and_b32 s34, s54, 7
	s_lshl_b32 s34, s34, 6
	s_lshl_b32 s35, s55, 12
	s_add_u32 s34, s34, s35
	s_add_u32 s32, s10, s34
	s_addc_u32 s33, s11, 0
	s_lshl_b32 s34, s53, 9
	v_add_u32_e32 v216, s34, v223
	ds_read_b128 v[80:83], v216 offset:0
	ds_read_b128 v[84:87], v216 offset:16
	ds_read_b128 v[88:91], v216 offset:32
	ds_read_b128 v[92:95], v216 offset:48
	s_waitcnt lgkmcnt(0)
	global_load_dwordx2 v[236:237], v234, s[32:33]
	v_mad_u32_u24 v217, v80, s52, v220
	v_add_u32_e32 v218, v217, v221
	global_load_dwordx4 v[96:99], v217, s[30:31]
	global_load_dwordx2 v[100:101], v218, s[30:31]
	v_mad_u32_u24 v217, v81, s52, v220
	v_add_u32_e32 v218, v217, v221
	global_load_dwordx4 v[102:105], v217, s[30:31]
	global_load_dwordx2 v[106:107], v218, s[30:31]
	v_mad_u32_u24 v217, v82, s52, v220
	v_add_u32_e32 v218, v217, v221
	global_load_dwordx4 v[108:111], v217, s[30:31]
	global_load_dwordx2 v[112:113], v218, s[30:31]
	v_mad_u32_u24 v217, v83, s52, v220
	v_add_u32_e32 v218, v217, v221
	global_load_dwordx4 v[114:117], v217, s[30:31]
	global_load_dwordx2 v[118:119], v218, s[30:31]
	v_mad_u32_u24 v217, v84, s52, v220
	v_add_u32_e32 v218, v217, v221
	global_load_dwordx4 v[120:123], v217, s[30:31]
	global_load_dwordx2 v[124:125], v218, s[30:31]
	v_mad_u32_u24 v217, v85, s52, v220
	v_add_u32_e32 v218, v217, v221
	global_load_dwordx4 v[126:129], v217, s[30:31]
	global_load_dwordx2 v[130:131], v218, s[30:31]
	v_mad_u32_u24 v217, v86, s52, v220
	v_add_u32_e32 v218, v217, v221
	global_load_dwordx4 v[132:135], v217, s[30:31]
	global_load_dwordx2 v[136:137], v218, s[30:31]
	v_mad_u32_u24 v217, v87, s52, v220
	v_add_u32_e32 v218, v217, v221
	global_load_dwordx4 v[138:141], v217, s[30:31]
	global_load_dwordx2 v[142:143], v218, s[30:31]
	v_mad_u32_u24 v217, v88, s52, v220
	v_add_u32_e32 v218, v217, v221
	global_load_dwordx4 v[144:147], v217, s[30:31]
	global_load_dwordx2 v[148:149], v218, s[30:31]
	v_mad_u32_u24 v217, v89, s52, v220
	v_add_u32_e32 v218, v217, v221
	global_load_dwordx4 v[150:153], v217, s[30:31]
	global_load_dwordx2 v[154:155], v218, s[30:31]
	v_mad_u32_u24 v217, v90, s52, v220
	v_add_u32_e32 v218, v217, v221
	global_load_dwordx4 v[156:159], v217, s[30:31]
	global_load_dwordx2 v[160:161], v218, s[30:31]
	v_mad_u32_u24 v217, v91, s52, v220
	v_add_u32_e32 v218, v217, v221
	global_load_dwordx4 v[162:165], v217, s[30:31]
	global_load_dwordx2 v[166:167], v218, s[30:31]
	v_mad_u32_u24 v217, v92, s52, v220
	v_add_u32_e32 v218, v217, v221
	global_load_dwordx4 v[168:171], v217, s[30:31]
	global_load_dwordx2 v[172:173], v218, s[30:31]
	v_mad_u32_u24 v217, v93, s52, v220
	v_add_u32_e32 v218, v217, v221
	global_load_dwordx4 v[174:177], v217, s[30:31]
	global_load_dwordx2 v[178:179], v218, s[30:31]
	v_mad_u32_u24 v217, v94, s52, v220
	v_add_u32_e32 v218, v217, v221
	global_load_dwordx4 v[180:183], v217, s[30:31]
	global_load_dwordx2 v[184:185], v218, s[30:31]
	v_mad_u32_u24 v217, v95, s52, v220
	v_add_u32_e32 v218, v217, v221
	global_load_dwordx4 v[186:189], v217, s[30:31]
	global_load_dwordx2 v[190:191], v218, s[30:31]
	s_waitcnt vmcnt(32)
	ds_write_b64 v235, v[236:237]
	ds_read_b64 v[64:65], v248 offset:0
	ds_read_b64 v[66:67], v248 offset:64
	ds_read_b64 v[68:69], v248 offset:128
	ds_read_b64 v[70:71], v248 offset:192
	ds_read_b64 v[72:73], v248 offset:256
	ds_read_b64 v[74:75], v248 offset:320
	ds_read_b64 v[76:77], v248 offset:384
	ds_read_b64 v[78:79], v248 offset:448
	s_add_i32 s53, s7, 1
	s_mov_b32 s54, s8
	s_cmp_eq_u32 s53, 8
	s_cselect_b32 s53, 0, s53
	s_cselect_b32 s34, 1, 0
	s_add_i32 s54, s54, s34
	s_mul_i32 s55, s53, s5
	s_add_i32 s55, s55, s6
	s_min_u32 s55, s55, 0x3fff
	s_and_b32 s34, s54, 7
	s_mul_i32 s34, s34, 0x300000
	s_cmp_lt_u32 s54, 8
	s_cselect_b32 s30, s16, s18
	s_cselect_b32 s31, s17, s19
	s_add_u32 s30, s30, s34
	s_addc_u32 s31, s31, 0
	s_and_b32 s34, s54, 7
	s_lshl_b32 s34, s34, 6
	s_lshl_b32 s35, s55, 12
	s_add_u32 s34, s34, s35
	s_add_u32 s32, s10, s34
	s_addc_u32 s33, s11, 0
	s_lshl_b32 s34, s53, 9
	v_add_u32_e32 v216, s34, v223
	ds_read_b128 v[80:83], v216 offset:0
	ds_read_b128 v[84:87], v216 offset:16
	ds_read_b128 v[88:91], v216 offset:32
	ds_read_b128 v[92:95], v216 offset:48
	.p2align 6

.Lex_ufirst:
	ds_write_b64 v219, v[192:193]
	s_cmp_lt_u32 s8, 8
	s_cbranch_scc1 .Lex_uloop
	s_waitcnt vmcnt(0) lgkmcnt(0)
	ds_read_b64 v[96:97], v222 offset:4096
	ds_read_b64 v[98:99], v222 offset:0
	ds_read_b64 v[108:109], v222 offset:4608
	ds_read_b64 v[110:111], v222 offset:512
	ds_read_b64 v[120:121], v222 offset:5120
	ds_read_b64 v[122:123], v222 offset:1024
	ds_read_b64 v[132:133], v222 offset:5632
	ds_read_b64 v[134:135], v222 offset:1536
	ds_read_b64 v[144:145], v222 offset:6144
	ds_read_b64 v[146:147], v222 offset:2048
	ds_read_b64 v[156:157], v222 offset:6656
	ds_read_b64 v[158:159], v222 offset:2560
	ds_read_b64 v[168:169], v222 offset:7168
	ds_read_b64 v[170:171], v222 offset:3072
	ds_read_b64 v[180:181], v222 offset:7680
	ds_read_b64 v[182:183], v222 offset:3584
	s_waitcnt lgkmcnt(0)
	s_movk_i32 s36, 0
	s_mul_i32 s37, s36, s5
	s_add_i32 s37, s37, s6
	s_min_u32 s37, s37, 0x3fff
	s_lshl_b32 s37, s37, 9
	s_add_u32 s82, s14, s37
	s_addc_u32 s83, s15, 0
	v_lshlrev_b32_e32 v219, 3, v228
	global_load_dwordx2 v[100:101], v219, s[82:83]
	v_lshlrev_b32_e32 v217, 2, v98
	v_lshlrev_b32_e32 v218, 2, v99
	global_load_dword v102, v217, s[20:21]
	global_load_dword v103, v218, s[20:21]
	global_load_dword v104, v217, s[22:23]
	global_load_dword v105, v218, s[22:23]
	s_movk_i32 s36, 1
	s_mul_i32 s37, s36, s5
	s_add_i32 s37, s37, s6
	s_min_u32 s37, s37, 0x3fff
	s_lshl_b32 s37, s37, 9
	s_add_u32 s82, s14, s37
	s_addc_u32 s83, s15, 0
	v_lshlrev_b32_e32 v219, 3, v228
	global_load_dwordx2 v[112:113], v219, s[82:83]
	v_lshlrev_b32_e32 v217, 2, v110
	v_lshlrev_b32_e32 v218, 2, v111
	global_load_dword v114, v217, s[20:21]
	global_load_dword v115, v218, s[20:21]
	global_load_dword v116, v217, s[22:23]
	global_load_dword v117, v218, s[22:23]
	s_movk_i32 s36, 2
	s_mul_i32 s37, s36, s5
	s_add_i32 s37, s37, s6
	s_min_u32 s37, s37, 0x3fff
	s_lshl_b32 s37, s37, 9
	s_add_u32 s82, s14, s37
	s_addc_u32 s83, s15, 0
	v_lshlrev_b32_e32 v219, 3, v228
	global_load_dwordx2 v[124:125], v219, s[82:83]
	v_lshlrev_b32_e32 v217, 2, v122
	v_lshlrev_b32_e32 v218, 2, v123
	global_load_dword v126, v217, s[20:21]
	global_load_dword v127, v218, s[20:21]
	global_load_dword v128, v217, s[22:23]
	global_load_dword v129, v218, s[22:23]
	s_movk_i32 s36, 3
	s_mul_i32 s37, s36, s5
	s_add_i32 s37, s37, s6
	s_min_u32 s37, s37, 0x3fff
	s_lshl_b32 s37, s37, 9
	s_add_u32 s82, s14, s37
	s_addc_u32 s83, s15, 0
	v_lshlrev_b32_e32 v219, 3, v228
	global_load_dwordx2 v[136:137], v219, s[82:83]
	v_lshlrev_b32_e32 v217, 2, v134
	v_lshlrev_b32_e32 v218, 2, v135
	global_load_dword v138, v217, s[20:21]
	global_load_dword v139, v218, s[20:21]
	global_load_dword v140, v217, s[22:23]
	global_load_dword v141, v218, s[22:23]
	s_movk_i32 s36, 4
	s_mul_i32 s37, s36, s5
	s_add_i32 s37, s37, s6
	s_min_u32 s37, s37, 0x3fff
	s_lshl_b32 s37, s37, 9
	s_add_u32 s82, s14, s37
	s_addc_u32 s83, s15, 0
	v_lshlrev_b32_e32 v219, 3, v228
	global_load_dwordx2 v[148:149], v219, s[82:83]
	v_lshlrev_b32_e32 v217, 2, v146
	v_lshlrev_b32_e32 v218, 2, v147
	global_load_dword v150, v217, s[20:21]
	global_load_dword v151, v218, s[20:21]
	global_load_dword v152, v217, s[22:23]
	global_load_dword v153, v218, s[22:23]
	s_movk_i32 s36, 5
	s_mul_i32 s37, s36, s5
	s_add_i32 s37, s37, s6
	s_min_u32 s37, s37, 0x3fff
	s_lshl_b32 s37, s37, 9
	s_add_u32 s82, s14, s37
	s_addc_u32 s83, s15, 0
	v_lshlrev_b32_e32 v219, 3, v228
	global_load_dwordx2 v[160:161], v219, s[82:83]
	v_lshlrev_b32_e32 v217, 2, v158
	v_lshlrev_b32_e32 v218, 2, v159
	global_load_dword v162, v217, s[20:21]
	global_load_dword v163, v218, s[20:21]
	global_load_dword v164, v217, s[22:23]
	global_load_dword v165, v218, s[22:23]
	s_movk_i32 s36, 6
	s_mul_i32 s37, s36, s5
	s_add_i32 s37, s37, s6
	s_min_u32 s37, s37, 0x3fff
	s_lshl_b32 s37, s37, 9
	s_add_u32 s82, s14, s37
	s_addc_u32 s83, s15, 0
	v_lshlrev_b32_e32 v219, 3, v228
	global_load_dwordx2 v[172:173], v219, s[82:83]
	v_lshlrev_b32_e32 v217, 2, v170
	v_lshlrev_b32_e32 v218, 2, v171
	global_load_dword v174, v217, s[20:21]
	global_load_dword v175, v218, s[20:21]
	global_load_dword v176, v217, s[22:23]
	global_load_dword v177, v218, s[22:23]
	s_movk_i32 s36, 7
	s_mul_i32 s37, s36, s5
	s_add_i32 s37, s37, s6
	s_min_u32 s37, s37, 0x3fff
	s_lshl_b32 s37, s37, 9
	s_add_u32 s82, s14, s37
	s_addc_u32 s83, s15, 0
	v_lshlrev_b32_e32 v219, 3, v228
	global_load_dwordx2 v[184:185], v219, s[82:83]
	v_lshlrev_b32_e32 v217, 2, v182
	v_lshlrev_b32_e32 v218, 2, v183
	global_load_dword v186, v217, s[20:21]
	global_load_dword v187, v218, s[20:21]
	global_load_dword v188, v217, s[22:23]
	global_load_dword v189, v218, s[22:23]
	s_waitcnt vmcnt(0)
	v_mul_f32_e32 v96, v102, v96
	v_mul_f32_e32 v0, 0x3f3504f3, v96
	v_mov_b32_e32 v6, s67
	v_fma_f32 v2, |v0|, s66, v6
	v_fma_f32 v2, |v0|, v2, s68
	v_fma_f32 v2, |v0|, v2, s69
	v_fma_f32 v2, |v0|, v2, s70
	v_fma_f32 v2, |v0|, v2, s71
	v_fma_f32 v2, |v0|, v2, s72
	v_fma_f32 v2, |v0|, v2, |v0|
	v_mul_f32_e32 v4, 0xbfb8aa3b, v2
	v_fma_f32 v5, v2, s73, -v4
	v_rndne_f32_e32 v6, v4
	v_fmac_f32_e32 v5, 0xb2a5705f, v2
	v_sub_f32_e32 v4, v4, v6
	v_add_f32_e32 v4, v4, v5
	v_cvt_i32_f32_e32 v5, v6
	v_exp_f32_e32 v4, v4
	v_cmp_nlt_f32_e64 s[82:83], s74, v2
	v_ldexp_f32 v4, v4, v5
	s_nop 0
	v_cndmask_b32_e64 v4, 0, v4, s[82:83]
	v_cmp_ngt_f32_e64 s[82:83], s75, v2
	v_mov_b32_e32 v6, 0x7f800000
	s_nop 0
	v_cndmask_b32_e64 v3, v6, v4, s[82:83]
	v_sub_f32_e32 v3, 1.0, v3
	v_mul_f32_e32 v4, v0, v0
	v_mov_b32_e32 v6, s76
	v_fmamk_f32 v5, v4, 0xba1345e1, v6
	v_fmaak_f32 v5, v4, v5, 0xbcdac9b8
	v_fmaak_f32 v5, v4, v5, 0x3de703be
	v_fmaak_f32 v5, v4, v5, 0xbec09330
	v_fmaak_f32 v4, v4, v5, 0x3e0375d0
	v_fma_f32 v7, |v0|, v4, |v0|
	v_cmp_nlt_f32_e64 s[82:83], |v0|, 1.0
	s_nop 1
	v_cndmask_b32_e64 v3, v7, v3, s[82:83]
	v_bfi_b32 v3, s77, v3, v0
	v_mul_f32_e32 v96, 0.5, v96
	v_add_f32_e32 v3, 1.0, v3
	v_mul_f32_e32 v96, v96, v3
	v_mul_f32_e32 v96, v96, v100
	v_mul_f32_e32 v96, v104, v96
	v_mul_f32_e32 v97, v103, v97
	v_mul_f32_e32 v0, 0x3f3504f3, v97
	v_mov_b32_e32 v6, s67
	v_fma_f32 v2, |v0|, s66, v6
	v_fma_f32 v2, |v0|, v2, s68
	v_fma_f32 v2, |v0|, v2, s69
	v_fma_f32 v2, |v0|, v2, s70
	v_fma_f32 v2, |v0|, v2, s71
	v_fma_f32 v2, |v0|, v2, s72
	v_fma_f32 v2, |v0|, v2, |v0|
	v_mul_f32_e32 v4, 0xbfb8aa3b, v2
	v_fma_f32 v5, v2, s73, -v4
	v_rndne_f32_e32 v6, v4
	v_fmac_f32_e32 v5, 0xb2a5705f, v2
	v_sub_f32_e32 v4, v4, v6
	v_add_f32_e32 v4, v4, v5
	v_cvt_i32_f32_e32 v5, v6
	v_exp_f32_e32 v4, v4
	v_cmp_nlt_f32_e64 s[82:83], s74, v2
	v_ldexp_f32 v4, v4, v5
	s_nop 0
	v_cndmask_b32_e64 v4, 0, v4, s[82:83]
	v_cmp_ngt_f32_e64 s[82:83], s75, v2
	v_mov_b32_e32 v6, 0x7f800000
	s_nop 0
	v_cndmask_b32_e64 v3, v6, v4, s[82:83]
	v_sub_f32_e32 v3, 1.0, v3
	v_mul_f32_e32 v4, v0, v0
	v_mov_b32_e32 v6, s76
	v_fmamk_f32 v5, v4, 0xba1345e1, v6
	v_fmaak_f32 v5, v4, v5, 0xbcdac9b8
	v_fmaak_f32 v5, v4, v5, 0x3de703be
	v_fmaak_f32 v5, v4, v5, 0xbec09330
	v_fmaak_f32 v4, v4, v5, 0x3e0375d0
	v_fma_f32 v7, |v0|, v4, |v0|
	v_cmp_nlt_f32_e64 s[82:83], |v0|, 1.0
	s_nop 1
	v_cndmask_b32_e64 v3, v7, v3, s[82:83]
	v_bfi_b32 v3, s77, v3, v0
	v_mul_f32_e32 v97, 0.5, v97
	v_add_f32_e32 v3, 1.0, v3
	v_mul_f32_e32 v97, v97, v3
	v_mul_f32_e32 v97, v97, v101
	v_mul_f32_e32 v97, v105, v97
	ds_write_b64 v222, v[96:97] offset:4096
	v_mul_f32_e32 v108, v114, v108
	v_mul_f32_e32 v0, 0x3f3504f3, v108
	v_mov_b32_e32 v6, s67
	v_fma_f32 v2, |v0|, s66, v6
	v_fma_f32 v2, |v0|, v2, s68
	v_fma_f32 v2, |v0|, v2, s69
	v_fma_f32 v2, |v0|, v2, s70
	v_fma_f32 v2, |v0|, v2, s71
	v_fma_f32 v2, |v0|, v2, s72
	v_fma_f32 v2, |v0|, v2, |v0|
	v_mul_f32_e32 v4, 0xbfb8aa3b, v2
	v_fma_f32 v5, v2, s73, -v4
	v_rndne_f32_e32 v6, v4
	v_fmac_f32_e32 v5, 0xb2a5705f, v2
	v_sub_f32_e32 v4, v4, v6
	v_add_f32_e32 v4, v4, v5
	v_cvt_i32_f32_e32 v5, v6
	v_exp_f32_e32 v4, v4
	v_cmp_nlt_f32_e64 s[82:83], s74, v2
	v_ldexp_f32 v4, v4, v5
	s_nop 0
	v_cndmask_b32_e64 v4, 0, v4, s[82:83]
	v_cmp_ngt_f32_e64 s[82:83], s75, v2
	v_mov_b32_e32 v6, 0x7f800000
	s_nop 0
	v_cndmask_b32_e64 v3, v6, v4, s[82:83]
	v_sub_f32_e32 v3, 1.0, v3
	v_mul_f32_e32 v4, v0, v0
	v_mov_b32_e32 v6, s76
	v_fmamk_f32 v5, v4, 0xba1345e1, v6
	v_fmaak_f32 v5, v4, v5, 0xbcdac9b8
	v_fmaak_f32 v5, v4, v5, 0x3de703be
	v_fmaak_f32 v5, v4, v5, 0xbec09330
	v_fmaak_f32 v4, v4, v5, 0x3e0375d0
	v_fma_f32 v7, |v0|, v4, |v0|
	v_cmp_nlt_f32_e64 s[82:83], |v0|, 1.0
	s_nop 1
	v_cndmask_b32_e64 v3, v7, v3, s[82:83]
	v_bfi_b32 v3, s77, v3, v0
	v_mul_f32_e32 v108, 0.5, v108
	v_add_f32_e32 v3, 1.0, v3
	v_mul_f32_e32 v108, v108, v3
	v_mul_f32_e32 v108, v108, v112
	v_mul_f32_e32 v108, v116, v108
	v_mul_f32_e32 v109, v115, v109
	v_mul_f32_e32 v0, 0x3f3504f3, v109
	v_mov_b32_e32 v6, s67
	v_fma_f32 v2, |v0|, s66, v6
	v_fma_f32 v2, |v0|, v2, s68
	v_fma_f32 v2, |v0|, v2, s69
	v_fma_f32 v2, |v0|, v2, s70
	v_fma_f32 v2, |v0|, v2, s71
	v_fma_f32 v2, |v0|, v2, s72
	v_fma_f32 v2, |v0|, v2, |v0|
	v_mul_f32_e32 v4, 0xbfb8aa3b, v2
	v_fma_f32 v5, v2, s73, -v4
	v_rndne_f32_e32 v6, v4
	v_fmac_f32_e32 v5, 0xb2a5705f, v2
	v_sub_f32_e32 v4, v4, v6
	v_add_f32_e32 v4, v4, v5
	v_cvt_i32_f32_e32 v5, v6
	v_exp_f32_e32 v4, v4
	v_cmp_nlt_f32_e64 s[82:83], s74, v2
	v_ldexp_f32 v4, v4, v5
	s_nop 0
	v_cndmask_b32_e64 v4, 0, v4, s[82:83]
	v_cmp_ngt_f32_e64 s[82:83], s75, v2
	v_mov_b32_e32 v6, 0x7f800000
	s_nop 0
	v_cndmask_b32_e64 v3, v6, v4, s[82:83]
	v_sub_f32_e32 v3, 1.0, v3
	v_mul_f32_e32 v4, v0, v0
	v_mov_b32_e32 v6, s76
	v_fmamk_f32 v5, v4, 0xba1345e1, v6
	v_fmaak_f32 v5, v4, v5, 0xbcdac9b8
	v_fmaak_f32 v5, v4, v5, 0x3de703be
	v_fmaak_f32 v5, v4, v5, 0xbec09330
	v_fmaak_f32 v4, v4, v5, 0x3e0375d0
	v_fma_f32 v7, |v0|, v4, |v0|
	v_cmp_nlt_f32_e64 s[82:83], |v0|, 1.0
	s_nop 1
	v_cndmask_b32_e64 v3, v7, v3, s[82:83]
	v_bfi_b32 v3, s77, v3, v0
	v_mul_f32_e32 v109, 0.5, v109
	v_add_f32_e32 v3, 1.0, v3
	v_mul_f32_e32 v109, v109, v3
	v_mul_f32_e32 v109, v109, v113
	v_mul_f32_e32 v109, v117, v109
	ds_write_b64 v222, v[108:109] offset:4608
	v_mul_f32_e32 v120, v126, v120
	v_mul_f32_e32 v0, 0x3f3504f3, v120
	v_mov_b32_e32 v6, s67
	v_fma_f32 v2, |v0|, s66, v6
	v_fma_f32 v2, |v0|, v2, s68
	v_fma_f32 v2, |v0|, v2, s69
	v_fma_f32 v2, |v0|, v2, s70
	v_fma_f32 v2, |v0|, v2, s71
	v_fma_f32 v2, |v0|, v2, s72
	v_fma_f32 v2, |v0|, v2, |v0|
	v_mul_f32_e32 v4, 0xbfb8aa3b, v2
	v_fma_f32 v5, v2, s73, -v4
	v_rndne_f32_e32 v6, v4
	v_fmac_f32_e32 v5, 0xb2a5705f, v2
	v_sub_f32_e32 v4, v4, v6
	v_add_f32_e32 v4, v4, v5
	v_cvt_i32_f32_e32 v5, v6
	v_exp_f32_e32 v4, v4
	v_cmp_nlt_f32_e64 s[82:83], s74, v2
	v_ldexp_f32 v4, v4, v5
	s_nop 0
	v_cndmask_b32_e64 v4, 0, v4, s[82:83]
	v_cmp_ngt_f32_e64 s[82:83], s75, v2
	v_mov_b32_e32 v6, 0x7f800000
	s_nop 0
	v_cndmask_b32_e64 v3, v6, v4, s[82:83]
	v_sub_f32_e32 v3, 1.0, v3
	v_mul_f32_e32 v4, v0, v0
	v_mov_b32_e32 v6, s76
	v_fmamk_f32 v5, v4, 0xba1345e1, v6
	v_fmaak_f32 v5, v4, v5, 0xbcdac9b8
	v_fmaak_f32 v5, v4, v5, 0x3de703be
	v_fmaak_f32 v5, v4, v5, 0xbec09330
	v_fmaak_f32 v4, v4, v5, 0x3e0375d0
	v_fma_f32 v7, |v0|, v4, |v0|
	v_cmp_nlt_f32_e64 s[82:83], |v0|, 1.0
	s_nop 1
	v_cndmask_b32_e64 v3, v7, v3, s[82:83]
	v_bfi_b32 v3, s77, v3, v0
	v_mul_f32_e32 v120, 0.5, v120
	v_add_f32_e32 v3, 1.0, v3
	v_mul_f32_e32 v120, v120, v3
	v_mul_f32_e32 v120, v120, v124
	v_mul_f32_e32 v120, v128, v120
	v_mul_f32_e32 v121, v127, v121
	v_mul_f32_e32 v0, 0x3f3504f3, v121
	v_mov_b32_e32 v6, s67
	v_fma_f32 v2, |v0|, s66, v6
	v_fma_f32 v2, |v0|, v2, s68
	v_fma_f32 v2, |v0|, v2, s69
	v_fma_f32 v2, |v0|, v2, s70
	v_fma_f32 v2, |v0|, v2, s71
	v_fma_f32 v2, |v0|, v2, s72
	v_fma_f32 v2, |v0|, v2, |v0|
	v_mul_f32_e32 v4, 0xbfb8aa3b, v2
	v_fma_f32 v5, v2, s73, -v4
	v_rndne_f32_e32 v6, v4
	v_fmac_f32_e32 v5, 0xb2a5705f, v2
	v_sub_f32_e32 v4, v4, v6
	v_add_f32_e32 v4, v4, v5
	v_cvt_i32_f32_e32 v5, v6
	v_exp_f32_e32 v4, v4
	v_cmp_nlt_f32_e64 s[82:83], s74, v2
	v_ldexp_f32 v4, v4, v5
	s_nop 0
	v_cndmask_b32_e64 v4, 0, v4, s[82:83]
	v_cmp_ngt_f32_e64 s[82:83], s75, v2
	v_mov_b32_e32 v6, 0x7f800000
	s_nop 0
	v_cndmask_b32_e64 v3, v6, v4, s[82:83]
	v_sub_f32_e32 v3, 1.0, v3
	v_mul_f32_e32 v4, v0, v0
	v_mov_b32_e32 v6, s76
	v_fmamk_f32 v5, v4, 0xba1345e1, v6
	v_fmaak_f32 v5, v4, v5, 0xbcdac9b8
	v_fmaak_f32 v5, v4, v5, 0x3de703be
	v_fmaak_f32 v5, v4, v5, 0xbec09330
	v_fmaak_f32 v4, v4, v5, 0x3e0375d0
	v_fma_f32 v7, |v0|, v4, |v0|
	v_cmp_nlt_f32_e64 s[82:83], |v0|, 1.0
	s_nop 1
	v_cndmask_b32_e64 v3, v7, v3, s[82:83]
	v_bfi_b32 v3, s77, v3, v0
	v_mul_f32_e32 v121, 0.5, v121
	v_add_f32_e32 v3, 1.0, v3
	v_mul_f32_e32 v121, v121, v3
	v_mul_f32_e32 v121, v121, v125
	v_mul_f32_e32 v121, v129, v121
	ds_write_b64 v222, v[120:121] offset:5120
	v_mul_f32_e32 v132, v138, v132
	v_mul_f32_e32 v0, 0x3f3504f3, v132
	v_mov_b32_e32 v6, s67
	v_fma_f32 v2, |v0|, s66, v6
	v_fma_f32 v2, |v0|, v2, s68
	v_fma_f32 v2, |v0|, v2, s69
	v_fma_f32 v2, |v0|, v2, s70
	v_fma_f32 v2, |v0|, v2, s71
	v_fma_f32 v2, |v0|, v2, s72
	v_fma_f32 v2, |v0|, v2, |v0|
	v_mul_f32_e32 v4, 0xbfb8aa3b, v2
	v_fma_f32 v5, v2, s73, -v4
	v_rndne_f32_e32 v6, v4
	v_fmac_f32_e32 v5, 0xb2a5705f, v2
	v_sub_f32_e32 v4, v4, v6
	v_add_f32_e32 v4, v4, v5
	v_cvt_i32_f32_e32 v5, v6
	v_exp_f32_e32 v4, v4
	v_cmp_nlt_f32_e64 s[82:83], s74, v2
	v_ldexp_f32 v4, v4, v5
	s_nop 0
	v_cndmask_b32_e64 v4, 0, v4, s[82:83]
	v_cmp_ngt_f32_e64 s[82:83], s75, v2
	v_mov_b32_e32 v6, 0x7f800000
	s_nop 0
	v_cndmask_b32_e64 v3, v6, v4, s[82:83]
	v_sub_f32_e32 v3, 1.0, v3
	v_mul_f32_e32 v4, v0, v0
	v_mov_b32_e32 v6, s76
	v_fmamk_f32 v5, v4, 0xba1345e1, v6
	v_fmaak_f32 v5, v4, v5, 0xbcdac9b8
	v_fmaak_f32 v5, v4, v5, 0x3de703be
	v_fmaak_f32 v5, v4, v5, 0xbec09330
	v_fmaak_f32 v4, v4, v5, 0x3e0375d0
	v_fma_f32 v7, |v0|, v4, |v0|
	v_cmp_nlt_f32_e64 s[82:83], |v0|, 1.0
	s_nop 1
	v_cndmask_b32_e64 v3, v7, v3, s[82:83]
	v_bfi_b32 v3, s77, v3, v0
	v_mul_f32_e32 v132, 0.5, v132
	v_add_f32_e32 v3, 1.0, v3
	v_mul_f32_e32 v132, v132, v3
	v_mul_f32_e32 v132, v132, v136
	v_mul_f32_e32 v132, v140, v132
	v_mul_f32_e32 v133, v139, v133
	v_mul_f32_e32 v0, 0x3f3504f3, v133
	v_mov_b32_e32 v6, s67
	v_fma_f32 v2, |v0|, s66, v6
	v_fma_f32 v2, |v0|, v2, s68
	v_fma_f32 v2, |v0|, v2, s69
	v_fma_f32 v2, |v0|, v2, s70
	v_fma_f32 v2, |v0|, v2, s71
	v_fma_f32 v2, |v0|, v2, s72
	v_fma_f32 v2, |v0|, v2, |v0|
	v_mul_f32_e32 v4, 0xbfb8aa3b, v2
	v_fma_f32 v5, v2, s73, -v4
	v_rndne_f32_e32 v6, v4
	v_fmac_f32_e32 v5, 0xb2a5705f, v2
	v_sub_f32_e32 v4, v4, v6
	v_add_f32_e32 v4, v4, v5
	v_cvt_i32_f32_e32 v5, v6
	v_exp_f32_e32 v4, v4
	v_cmp_nlt_f32_e64 s[82:83], s74, v2
	v_ldexp_f32 v4, v4, v5
	s_nop 0
	v_cndmask_b32_e64 v4, 0, v4, s[82:83]
	v_cmp_ngt_f32_e64 s[82:83], s75, v2
	v_mov_b32_e32 v6, 0x7f800000
	s_nop 0
	v_cndmask_b32_e64 v3, v6, v4, s[82:83]
	v_sub_f32_e32 v3, 1.0, v3
	v_mul_f32_e32 v4, v0, v0
	v_mov_b32_e32 v6, s76
	v_fmamk_f32 v5, v4, 0xba1345e1, v6
	v_fmaak_f32 v5, v4, v5, 0xbcdac9b8
	v_fmaak_f32 v5, v4, v5, 0x3de703be
	v_fmaak_f32 v5, v4, v5, 0xbec09330
	v_fmaak_f32 v4, v4, v5, 0x3e0375d0
	v_fma_f32 v7, |v0|, v4, |v0|
	v_cmp_nlt_f32_e64 s[82:83], |v0|, 1.0
	s_nop 1
	v_cndmask_b32_e64 v3, v7, v3, s[82:83]
	v_bfi_b32 v3, s77, v3, v0
	v_mul_f32_e32 v133, 0.5, v133
	v_add_f32_e32 v3, 1.0, v3
	v_mul_f32_e32 v133, v133, v3
	v_mul_f32_e32 v133, v133, v137
	v_mul_f32_e32 v133, v141, v133
	ds_write_b64 v222, v[132:133] offset:5632
	v_mul_f32_e32 v144, v150, v144
	v_mul_f32_e32 v0, 0x3f3504f3, v144
	v_mov_b32_e32 v6, s67
	v_fma_f32 v2, |v0|, s66, v6
	v_fma_f32 v2, |v0|, v2, s68
	v_fma_f32 v2, |v0|, v2, s69
	v_fma_f32 v2, |v0|, v2, s70
	v_fma_f32 v2, |v0|, v2, s71
	v_fma_f32 v2, |v0|, v2, s72
	v_fma_f32 v2, |v0|, v2, |v0|
	v_mul_f32_e32 v4, 0xbfb8aa3b, v2
	v_fma_f32 v5, v2, s73, -v4
	v_rndne_f32_e32 v6, v4
	v_fmac_f32_e32 v5, 0xb2a5705f, v2
	v_sub_f32_e32 v4, v4, v6
	v_add_f32_e32 v4, v4, v5
	v_cvt_i32_f32_e32 v5, v6
	v_exp_f32_e32 v4, v4
	v_cmp_nlt_f32_e64 s[82:83], s74, v2
	v_ldexp_f32 v4, v4, v5
	s_nop 0
	v_cndmask_b32_e64 v4, 0, v4, s[82:83]
	v_cmp_ngt_f32_e64 s[82:83], s75, v2
	v_mov_b32_e32 v6, 0x7f800000
	s_nop 0
	v_cndmask_b32_e64 v3, v6, v4, s[82:83]
	v_sub_f32_e32 v3, 1.0, v3
	v_mul_f32_e32 v4, v0, v0
	v_mov_b32_e32 v6, s76
	v_fmamk_f32 v5, v4, 0xba1345e1, v6
	v_fmaak_f32 v5, v4, v5, 0xbcdac9b8
	v_fmaak_f32 v5, v4, v5, 0x3de703be
	v_fmaak_f32 v5, v4, v5, 0xbec09330
	v_fmaak_f32 v4, v4, v5, 0x3e0375d0
	v_fma_f32 v7, |v0|, v4, |v0|
	v_cmp_nlt_f32_e64 s[82:83], |v0|, 1.0
	s_nop 1
	v_cndmask_b32_e64 v3, v7, v3, s[82:83]
	v_bfi_b32 v3, s77, v3, v0
	v_mul_f32_e32 v144, 0.5, v144
	v_add_f32_e32 v3, 1.0, v3
	v_mul_f32_e32 v144, v144, v3
	v_mul_f32_e32 v144, v144, v148
	v_mul_f32_e32 v144, v152, v144
	v_mul_f32_e32 v145, v151, v145
	v_mul_f32_e32 v0, 0x3f3504f3, v145
	v_mov_b32_e32 v6, s67
	v_fma_f32 v2, |v0|, s66, v6
	v_fma_f32 v2, |v0|, v2, s68
	v_fma_f32 v2, |v0|, v2, s69
	v_fma_f32 v2, |v0|, v2, s70
	v_fma_f32 v2, |v0|, v2, s71
	v_fma_f32 v2, |v0|, v2, s72
	v_fma_f32 v2, |v0|, v2, |v0|
	v_mul_f32_e32 v4, 0xbfb8aa3b, v2
	v_fma_f32 v5, v2, s73, -v4
	v_rndne_f32_e32 v6, v4
	v_fmac_f32_e32 v5, 0xb2a5705f, v2
	v_sub_f32_e32 v4, v4, v6
	v_add_f32_e32 v4, v4, v5
	v_cvt_i32_f32_e32 v5, v6
	v_exp_f32_e32 v4, v4
	v_cmp_nlt_f32_e64 s[82:83], s74, v2
	v_ldexp_f32 v4, v4, v5
	s_nop 0
	v_cndmask_b32_e64 v4, 0, v4, s[82:83]
	v_cmp_ngt_f32_e64 s[82:83], s75, v2
	v_mov_b32_e32 v6, 0x7f800000
	s_nop 0
	v_cndmask_b32_e64 v3, v6, v4, s[82:83]
	v_sub_f32_e32 v3, 1.0, v3
	v_mul_f32_e32 v4, v0, v0
	v_mov_b32_e32 v6, s76
	v_fmamk_f32 v5, v4, 0xba1345e1, v6
	v_fmaak_f32 v5, v4, v5, 0xbcdac9b8
	v_fmaak_f32 v5, v4, v5, 0x3de703be
	v_fmaak_f32 v5, v4, v5, 0xbec09330
	v_fmaak_f32 v4, v4, v5, 0x3e0375d0
	v_fma_f32 v7, |v0|, v4, |v0|
	v_cmp_nlt_f32_e64 s[82:83], |v0|, 1.0
	s_nop 1
	v_cndmask_b32_e64 v3, v7, v3, s[82:83]
	v_bfi_b32 v3, s77, v3, v0
	v_mul_f32_e32 v145, 0.5, v145
	v_add_f32_e32 v3, 1.0, v3
	v_mul_f32_e32 v145, v145, v3
	v_mul_f32_e32 v145, v145, v149
	v_mul_f32_e32 v145, v153, v145
	ds_write_b64 v222, v[144:145] offset:6144
	v_mul_f32_e32 v156, v162, v156
	v_mul_f32_e32 v0, 0x3f3504f3, v156
	v_mov_b32_e32 v6, s67
	v_fma_f32 v2, |v0|, s66, v6
	v_fma_f32 v2, |v0|, v2, s68
	v_fma_f32 v2, |v0|, v2, s69
	v_fma_f32 v2, |v0|, v2, s70
	v_fma_f32 v2, |v0|, v2, s71
	v_fma_f32 v2, |v0|, v2, s72
	v_fma_f32 v2, |v0|, v2, |v0|
	v_mul_f32_e32 v4, 0xbfb8aa3b, v2
	v_fma_f32 v5, v2, s73, -v4
	v_rndne_f32_e32 v6, v4
	v_fmac_f32_e32 v5, 0xb2a5705f, v2
	v_sub_f32_e32 v4, v4, v6
	v_add_f32_e32 v4, v4, v5
	v_cvt_i32_f32_e32 v5, v6
	v_exp_f32_e32 v4, v4
	v_cmp_nlt_f32_e64 s[82:83], s74, v2
	v_ldexp_f32 v4, v4, v5
	s_nop 0
	v_cndmask_b32_e64 v4, 0, v4, s[82:83]
	v_cmp_ngt_f32_e64 s[82:83], s75, v2
	v_mov_b32_e32 v6, 0x7f800000
	s_nop 0
	v_cndmask_b32_e64 v3, v6, v4, s[82:83]
	v_sub_f32_e32 v3, 1.0, v3
	v_mul_f32_e32 v4, v0, v0
	v_mov_b32_e32 v6, s76
	v_fmamk_f32 v5, v4, 0xba1345e1, v6
	v_fmaak_f32 v5, v4, v5, 0xbcdac9b8
	v_fmaak_f32 v5, v4, v5, 0x3de703be
	v_fmaak_f32 v5, v4, v5, 0xbec09330
	v_fmaak_f32 v4, v4, v5, 0x3e0375d0
	v_fma_f32 v7, |v0|, v4, |v0|
	v_cmp_nlt_f32_e64 s[82:83], |v0|, 1.0
	s_nop 1
	v_cndmask_b32_e64 v3, v7, v3, s[82:83]
	v_bfi_b32 v3, s77, v3, v0
	v_mul_f32_e32 v156, 0.5, v156
	v_add_f32_e32 v3, 1.0, v3
	v_mul_f32_e32 v156, v156, v3
	v_mul_f32_e32 v156, v156, v160
	v_mul_f32_e32 v156, v164, v156
	v_mul_f32_e32 v157, v163, v157
	v_mul_f32_e32 v0, 0x3f3504f3, v157
	v_mov_b32_e32 v6, s67
	v_fma_f32 v2, |v0|, s66, v6
	v_fma_f32 v2, |v0|, v2, s68
	v_fma_f32 v2, |v0|, v2, s69
	v_fma_f32 v2, |v0|, v2, s70
	v_fma_f32 v2, |v0|, v2, s71
	v_fma_f32 v2, |v0|, v2, s72
	v_fma_f32 v2, |v0|, v2, |v0|
	v_mul_f32_e32 v4, 0xbfb8aa3b, v2
	v_fma_f32 v5, v2, s73, -v4
	v_rndne_f32_e32 v6, v4
	v_fmac_f32_e32 v5, 0xb2a5705f, v2
	v_sub_f32_e32 v4, v4, v6
	v_add_f32_e32 v4, v4, v5
	v_cvt_i32_f32_e32 v5, v6
	v_exp_f32_e32 v4, v4
	v_cmp_nlt_f32_e64 s[82:83], s74, v2
	v_ldexp_f32 v4, v4, v5
	s_nop 0
	v_cndmask_b32_e64 v4, 0, v4, s[82:83]
	v_cmp_ngt_f32_e64 s[82:83], s75, v2
	v_mov_b32_e32 v6, 0x7f800000
	s_nop 0
	v_cndmask_b32_e64 v3, v6, v4, s[82:83]
	v_sub_f32_e32 v3, 1.0, v3
	v_mul_f32_e32 v4, v0, v0
	v_mov_b32_e32 v6, s76
	v_fmamk_f32 v5, v4, 0xba1345e1, v6
	v_fmaak_f32 v5, v4, v5, 0xbcdac9b8
	v_fmaak_f32 v5, v4, v5, 0x3de703be
	v_fmaak_f32 v5, v4, v5, 0xbec09330
	v_fmaak_f32 v4, v4, v5, 0x3e0375d0
	v_fma_f32 v7, |v0|, v4, |v0|
	v_cmp_nlt_f32_e64 s[82:83], |v0|, 1.0
	s_nop 1
	v_cndmask_b32_e64 v3, v7, v3, s[82:83]
	v_bfi_b32 v3, s77, v3, v0
	v_mul_f32_e32 v157, 0.5, v157
	v_add_f32_e32 v3, 1.0, v3
	v_mul_f32_e32 v157, v157, v3
	v_mul_f32_e32 v157, v157, v161
	v_mul_f32_e32 v157, v165, v157
	ds_write_b64 v222, v[156:157] offset:6656
	v_mul_f32_e32 v168, v174, v168
	v_mul_f32_e32 v0, 0x3f3504f3, v168
	v_mov_b32_e32 v6, s67
	v_fma_f32 v2, |v0|, s66, v6
	v_fma_f32 v2, |v0|, v2, s68
	v_fma_f32 v2, |v0|, v2, s69
	v_fma_f32 v2, |v0|, v2, s70
	v_fma_f32 v2, |v0|, v2, s71
	v_fma_f32 v2, |v0|, v2, s72
	v_fma_f32 v2, |v0|, v2, |v0|
	v_mul_f32_e32 v4, 0xbfb8aa3b, v2
	v_fma_f32 v5, v2, s73, -v4
	v_rndne_f32_e32 v6, v4
	v_fmac_f32_e32 v5, 0xb2a5705f, v2
	v_sub_f32_e32 v4, v4, v6
	v_add_f32_e32 v4, v4, v5
	v_cvt_i32_f32_e32 v5, v6
	v_exp_f32_e32 v4, v4
	v_cmp_nlt_f32_e64 s[82:83], s74, v2
	v_ldexp_f32 v4, v4, v5
	s_nop 0
	v_cndmask_b32_e64 v4, 0, v4, s[82:83]
	v_cmp_ngt_f32_e64 s[82:83], s75, v2
	v_mov_b32_e32 v6, 0x7f800000
	s_nop 0
	v_cndmask_b32_e64 v3, v6, v4, s[82:83]
	v_sub_f32_e32 v3, 1.0, v3
	v_mul_f32_e32 v4, v0, v0
	v_mov_b32_e32 v6, s76
	v_fmamk_f32 v5, v4, 0xba1345e1, v6
	v_fmaak_f32 v5, v4, v5, 0xbcdac9b8
	v_fmaak_f32 v5, v4, v5, 0x3de703be
	v_fmaak_f32 v5, v4, v5, 0xbec09330
	v_fmaak_f32 v4, v4, v5, 0x3e0375d0
	v_fma_f32 v7, |v0|, v4, |v0|
	v_cmp_nlt_f32_e64 s[82:83], |v0|, 1.0
	s_nop 1
	v_cndmask_b32_e64 v3, v7, v3, s[82:83]
	v_bfi_b32 v3, s77, v3, v0
	v_mul_f32_e32 v168, 0.5, v168
	v_add_f32_e32 v3, 1.0, v3
	v_mul_f32_e32 v168, v168, v3
	v_mul_f32_e32 v168, v168, v172
	v_mul_f32_e32 v168, v176, v168
	v_mul_f32_e32 v169, v175, v169
	v_mul_f32_e32 v0, 0x3f3504f3, v169
	v_mov_b32_e32 v6, s67
	v_fma_f32 v2, |v0|, s66, v6
	v_fma_f32 v2, |v0|, v2, s68
	v_fma_f32 v2, |v0|, v2, s69
	v_fma_f32 v2, |v0|, v2, s70
	v_fma_f32 v2, |v0|, v2, s71
	v_fma_f32 v2, |v0|, v2, s72
	v_fma_f32 v2, |v0|, v2, |v0|
	v_mul_f32_e32 v4, 0xbfb8aa3b, v2
	v_fma_f32 v5, v2, s73, -v4
	v_rndne_f32_e32 v6, v4
	v_fmac_f32_e32 v5, 0xb2a5705f, v2
	v_sub_f32_e32 v4, v4, v6
	v_add_f32_e32 v4, v4, v5
	v_cvt_i32_f32_e32 v5, v6
	v_exp_f32_e32 v4, v4
	v_cmp_nlt_f32_e64 s[82:83], s74, v2
	v_ldexp_f32 v4, v4, v5
	s_nop 0
	v_cndmask_b32_e64 v4, 0, v4, s[82:83]
	v_cmp_ngt_f32_e64 s[82:83], s75, v2
	v_mov_b32_e32 v6, 0x7f800000
	s_nop 0
	v_cndmask_b32_e64 v3, v6, v4, s[82:83]
	v_sub_f32_e32 v3, 1.0, v3
	v_mul_f32_e32 v4, v0, v0
	v_mov_b32_e32 v6, s76
	v_fmamk_f32 v5, v4, 0xba1345e1, v6
	v_fmaak_f32 v5, v4, v5, 0xbcdac9b8
	v_fmaak_f32 v5, v4, v5, 0x3de703be
	v_fmaak_f32 v5, v4, v5, 0xbec09330
	v_fmaak_f32 v4, v4, v5, 0x3e0375d0
	v_fma_f32 v7, |v0|, v4, |v0|
	v_cmp_nlt_f32_e64 s[82:83], |v0|, 1.0
	s_nop 1
	v_cndmask_b32_e64 v3, v7, v3, s[82:83]
	v_bfi_b32 v3, s77, v3, v0
	v_mul_f32_e32 v169, 0.5, v169
	v_add_f32_e32 v3, 1.0, v3
	v_mul_f32_e32 v169, v169, v3
	v_mul_f32_e32 v169, v169, v173
	v_mul_f32_e32 v169, v177, v169
	ds_write_b64 v222, v[168:169] offset:7168
	v_mul_f32_e32 v180, v186, v180
	v_mul_f32_e32 v0, 0x3f3504f3, v180
	v_mov_b32_e32 v6, s67
	v_fma_f32 v2, |v0|, s66, v6
	v_fma_f32 v2, |v0|, v2, s68
	v_fma_f32 v2, |v0|, v2, s69
	v_fma_f32 v2, |v0|, v2, s70
	v_fma_f32 v2, |v0|, v2, s71
	v_fma_f32 v2, |v0|, v2, s72
	v_fma_f32 v2, |v0|, v2, |v0|
	v_mul_f32_e32 v4, 0xbfb8aa3b, v2
	v_fma_f32 v5, v2, s73, -v4
	v_rndne_f32_e32 v6, v4
	v_fmac_f32_e32 v5, 0xb2a5705f, v2
	v_sub_f32_e32 v4, v4, v6
	v_add_f32_e32 v4, v4, v5
	v_cvt_i32_f32_e32 v5, v6
	v_exp_f32_e32 v4, v4
	v_cmp_nlt_f32_e64 s[82:83], s74, v2
	v_ldexp_f32 v4, v4, v5
	s_nop 0
	v_cndmask_b32_e64 v4, 0, v4, s[82:83]
	v_cmp_ngt_f32_e64 s[82:83], s75, v2
	v_mov_b32_e32 v6, 0x7f800000
	s_nop 0
	v_cndmask_b32_e64 v3, v6, v4, s[82:83]
	v_sub_f32_e32 v3, 1.0, v3
	v_mul_f32_e32 v4, v0, v0
	v_mov_b32_e32 v6, s76
	v_fmamk_f32 v5, v4, 0xba1345e1, v6
	v_fmaak_f32 v5, v4, v5, 0xbcdac9b8
	v_fmaak_f32 v5, v4, v5, 0x3de703be
	v_fmaak_f32 v5, v4, v5, 0xbec09330
	v_fmaak_f32 v4, v4, v5, 0x3e0375d0
	v_fma_f32 v7, |v0|, v4, |v0|
	v_cmp_nlt_f32_e64 s[82:83], |v0|, 1.0
	s_nop 1
	v_cndmask_b32_e64 v3, v7, v3, s[82:83]
	v_bfi_b32 v3, s77, v3, v0
	v_mul_f32_e32 v180, 0.5, v180
	v_add_f32_e32 v3, 1.0, v3
	v_mul_f32_e32 v180, v180, v3
	v_mul_f32_e32 v180, v180, v184
	v_mul_f32_e32 v180, v188, v180
	v_mul_f32_e32 v181, v187, v181
	v_mul_f32_e32 v0, 0x3f3504f3, v181
	v_mov_b32_e32 v6, s67
	v_fma_f32 v2, |v0|, s66, v6
	v_fma_f32 v2, |v0|, v2, s68
	v_fma_f32 v2, |v0|, v2, s69
	v_fma_f32 v2, |v0|, v2, s70
	v_fma_f32 v2, |v0|, v2, s71
	v_fma_f32 v2, |v0|, v2, s72
	v_fma_f32 v2, |v0|, v2, |v0|
	v_mul_f32_e32 v4, 0xbfb8aa3b, v2
	v_fma_f32 v5, v2, s73, -v4
	v_rndne_f32_e32 v6, v4
	v_fmac_f32_e32 v5, 0xb2a5705f, v2
	v_sub_f32_e32 v4, v4, v6
	v_add_f32_e32 v4, v4, v5
	v_cvt_i32_f32_e32 v5, v6
	v_exp_f32_e32 v4, v4
	v_cmp_nlt_f32_e64 s[82:83], s74, v2
	v_ldexp_f32 v4, v4, v5
	s_nop 0
	v_cndmask_b32_e64 v4, 0, v4, s[82:83]
	v_cmp_ngt_f32_e64 s[82:83], s75, v2
	v_mov_b32_e32 v6, 0x7f800000
	s_nop 0
	v_cndmask_b32_e64 v3, v6, v4, s[82:83]
	v_sub_f32_e32 v3, 1.0, v3
	v_mul_f32_e32 v4, v0, v0
	v_mov_b32_e32 v6, s76
	v_fmamk_f32 v5, v4, 0xba1345e1, v6
	v_fmaak_f32 v5, v4, v5, 0xbcdac9b8
	v_fmaak_f32 v5, v4, v5, 0x3de703be
	v_fmaak_f32 v5, v4, v5, 0xbec09330
	v_fmaak_f32 v4, v4, v5, 0x3e0375d0
	v_fma_f32 v7, |v0|, v4, |v0|
	v_cmp_nlt_f32_e64 s[82:83], |v0|, 1.0
	s_nop 1
	v_cndmask_b32_e64 v3, v7, v3, s[82:83]
	v_bfi_b32 v3, s77, v3, v0
	v_mul_f32_e32 v181, 0.5, v181
	v_add_f32_e32 v3, 1.0, v3
	v_mul_f32_e32 v181, v181, v3
	v_mul_f32_e32 v181, v181, v185
	v_mul_f32_e32 v181, v189, v181
	ds_write_b64 v222, v[180:181] offset:7680
	s_waitcnt lgkmcnt(0)
	s_mov_b32 s8, 8
	s_mov_b32 s7, 0
	s_mov_b32 s54, 8
	s_mov_b32 s53, 0
	s_mul_i32 s55, s53, s5
	s_add_i32 s55, s55, s6
	s_min_u32 s55, s55, 0x3fff
	s_and_b32 s34, s54, 7
	s_mul_i32 s34, s34, 0x300000
	s_cmp_lt_u32 s54, 8
	s_cselect_b32 s30, s16, s18
	s_cselect_b32 s31, s17, s19
	s_add_u32 s30, s30, s34
	s_addc_u32 s31, s31, 0
	s_and_b32 s34, s54, 7
	s_lshl_b32 s34, s34, 6
	s_lshl_b32 s35, s55, 12
	s_add_u32 s34, s34, s35
	s_add_u32 s32, s24, s34
	s_addc_u32 s33, s25, 0
	s_and_b32 s34, s54, 7
	s_lshl_b32 s34, s34, 7
	s_lshr_b32 s35, s55, 13
	s_mul_i32 s35, s35, 0xc000
	s_add_u32 s35, s35, s34
	s_add_u32 s35, s35, 0xa000
	s_add_u32 s58, s26, s35
	s_addc_u32 s59, s27, 0
	s_lshl_b32 s35, s55, 13
	s_add_u32 s35, s35, s34
	s_add_u32 s60, s28, s35
	s_addc_u32 s61, s29, 0
	s_mul_i32 s34, s53, s5
	s_add_i32 s34, s34, s6
	s_cmp_lt_u32 s34, 0x4000
	s_cselect_b32 s57, 1, 0
	s_mov_b32 s78, s60
	s_mov_b32 s79, s61
	s_mov_b32 s80, s57
	s_lshl_b32 s34, s53, 9
	v_add_u32_e32 v216, s34, v223
	ds_read_b128 v[80:83], v216 offset:0
	ds_read_b128 v[84:87], v216 offset:16
	ds_read_b128 v[88:91], v216 offset:32
	ds_read_b128 v[92:95], v216 offset:48
	s_waitcnt lgkmcnt(0)
	global_load_dwordx2 v[64:65], v225, s[32:33]
	global_load_dwordx4 v[66:69], v226, s[58:59]
	v_mad_u32_u24 v217, v80, s52, v220
	v_add_u32_e32 v218, v217, v221
	global_load_dwordx4 v[96:99], v217, s[30:31]
	global_load_dwordx2 v[100:101], v218, s[30:31]
	v_mad_u32_u24 v217, v81, s52, v220
	v_add_u32_e32 v218, v217, v221
	global_load_dwordx4 v[102:105], v217, s[30:31]
	global_load_dwordx2 v[106:107], v218, s[30:31]
	v_mad_u32_u24 v217, v82, s52, v220
	v_add_u32_e32 v218, v217, v221
	global_load_dwordx4 v[108:111], v217, s[30:31]
	global_load_dwordx2 v[112:113], v218, s[30:31]
	v_mad_u32_u24 v217, v83, s52, v220
	v_add_u32_e32 v218, v217, v221
	global_load_dwordx4 v[114:117], v217, s[30:31]
	global_load_dwordx2 v[118:119], v218, s[30:31]
	v_mad_u32_u24 v217, v84, s52, v220
	v_add_u32_e32 v218, v217, v221
	global_load_dwordx4 v[120:123], v217, s[30:31]
	global_load_dwordx2 v[124:125], v218, s[30:31]
	v_mad_u32_u24 v217, v85, s52, v220
	v_add_u32_e32 v218, v217, v221
	global_load_dwordx4 v[126:129], v217, s[30:31]
	global_load_dwordx2 v[130:131], v218, s[30:31]
	v_mad_u32_u24 v217, v86, s52, v220
	v_add_u32_e32 v218, v217, v221
	global_load_dwordx4 v[132:135], v217, s[30:31]
	global_load_dwordx2 v[136:137], v218, s[30:31]
	v_mad_u32_u24 v217, v87, s52, v220
	v_add_u32_e32 v218, v217, v221
	global_load_dwordx4 v[138:141], v217, s[30:31]
	global_load_dwordx2 v[142:143], v218, s[30:31]
	v_mad_u32_u24 v217, v88, s52, v220
	v_add_u32_e32 v218, v217, v221
	global_load_dwordx4 v[144:147], v217, s[30:31]
	global_load_dwordx2 v[148:149], v218, s[30:31]
	v_mad_u32_u24 v217, v89, s52, v220
	v_add_u32_e32 v218, v217, v221
	global_load_dwordx4 v[150:153], v217, s[30:31]
	global_load_dwordx2 v[154:155], v218, s[30:31]
	v_mad_u32_u24 v217, v90, s52, v220
	v_add_u32_e32 v218, v217, v221
	global_load_dwordx4 v[156:159], v217, s[30:31]
	global_load_dwordx2 v[160:161], v218, s[30:31]
	v_mad_u32_u24 v217, v91, s52, v220
	v_add_u32_e32 v218, v217, v221
	global_load_dwordx4 v[162:165], v217, s[30:31]
	global_load_dwordx2 v[166:167], v218, s[30:31]
	v_mad_u32_u24 v217, v92, s52, v220
	v_add_u32_e32 v218, v217, v221
	global_load_dwordx4 v[168:171], v217, s[30:31]
	global_load_dwordx2 v[172:173], v218, s[30:31]
	v_mad_u32_u24 v217, v93, s52, v220
	v_add_u32_e32 v218, v217, v221
	global_load_dwordx4 v[174:177], v217, s[30:31]
	global_load_dwordx2 v[178:179], v218, s[30:31]
	v_mad_u32_u24 v217, v94, s52, v220
	v_add_u32_e32 v218, v217, v221
	global_load_dwordx4 v[180:183], v217, s[30:31]
	global_load_dwordx2 v[184:185], v218, s[30:31]
	v_mad_u32_u24 v217, v95, s52, v220
	v_add_u32_e32 v218, v217, v221
	global_load_dwordx4 v[186:189], v217, s[30:31]
	global_load_dwordx2 v[190:191], v218, s[30:31]
	global_load_dword v233, v231, s[28:29]
	s_add_i32 s53, s7, 1
	s_mov_b32 s54, s8
	s_cmp_eq_u32 s53, 8
	s_cselect_b32 s53, 0, s53
	s_cselect_b32 s34, 1, 0
	s_add_i32 s54, s54, s34
	s_mul_i32 s55, s53, s5
	s_add_i32 s55, s55, s6
	s_min_u32 s55, s55, 0x3fff
	s_and_b32 s34, s54, 7
	s_mul_i32 s34, s34, 0x300000
	s_cmp_lt_u32 s54, 8
	s_cselect_b32 s30, s16, s18
	s_cselect_b32 s31, s17, s19
	s_add_u32 s30, s30, s34
	s_addc_u32 s31, s31, 0
	s_and_b32 s34, s54, 7
	s_lshl_b32 s34, s34, 6
	s_lshl_b32 s35, s55, 12
	s_add_u32 s34, s34, s35
	s_add_u32 s32, s24, s34
	s_addc_u32 s33, s25, 0
	s_and_b32 s34, s54, 7
	s_lshl_b32 s34, s34, 7
	s_lshr_b32 s35, s55, 13
	s_mul_i32 s35, s35, 0xc000
	s_add_u32 s35, s35, s34
	s_add_u32 s35, s35, 0xa000
	s_add_u32 s58, s26, s35
	s_addc_u32 s59, s27, 0
	s_lshl_b32 s35, s55, 13
	s_add_u32 s35, s35, s34
	s_add_u32 s60, s28, s35
	s_addc_u32 s61, s29, 0
	s_mul_i32 s34, s53, s5
	s_add_i32 s34, s34, s6
	s_cmp_lt_u32 s34, 0x4000
	s_cselect_b32 s57, 1, 0
	s_lshl_b32 s34, s53, 9
	v_add_u32_e32 v216, s34, v223
	ds_read_b128 v[80:83], v216 offset:0
	ds_read_b128 v[84:87], v216 offset:16
	ds_read_b128 v[88:91], v216 offset:32
	ds_read_b128 v[92:95], v216 offset:48
	.p2align 6
